# P7a: T off-diagonal blocks via f32 MFMA column chains (no barriers), DPP forward substitution, precomputed zero-fill; grid.sync replaced by xcd barrier; deep-queue EpiResid
# speedup vs baseline: 1.0340x; 1.0238x over previous
; __device__ __forceinline__ int lane_now() { int l; asm volatile("v_mbcnt_lo_u32_b32 %0, -1, 0\n\tv_mbcnt_hi_u32_b32 %0, -1, %0" : "=v"(l)); return l; }
; __device__ __forceinline__ unsigned xb_ld(unsigned* p)              { return __hip_atomic_load(p, __ATOMIC_RELAXED, __HIP_MEMORY_SCOPE_AGENT); }
; __device__ __forceinline__ unsigned xb_add(unsigned* p, unsigned v) { return __hip_atomic_fetch_add(p, v, __ATOMIC_RELAXED, __HIP_MEMORY_SCOPE_AGENT); }
; #define XB_SPIN(cond, bar) do { unsigned _sp = 0; while (cond) { __builtin_amdgcn_s_sleep(1); \
;     if ((++_sp & 255u) == 0u) { if (xb_ld(&(bar)[XB_TMO])) break; if (_sp > XB_SPIN_CAP) { atomicAdd(&(bar)[XB_TMO], 1u); break; } } } } while (0)
; __device__ __forceinline__ void xcd_barrier(const XcdBarrier& b) {
;     asm volatile("s_waitcnt vmcnt(0)" ::: "memory");
;     __syncthreads();
;     if (b.w0 && lane_now() == 0) {
;         unsigned* bar = b.bar;
;         __builtin_amdgcn_s_waitcnt(0);
;         unsigned nloc = b.st[0], nx = b.st[1];
;         if (nloc == 0u) { xcd_barrier_complete(bar, b.x, nloc, nx); b.st[0] = nloc; b.st[1] = nx; }
;         const unsigned old = xb_add(&bar[XB_XSUB(b.x)], 1u);
;         const unsigned gen = old / nloc;
;         if (old + 1u == (gen + 1u) * nloc) {
;             __builtin_amdgcn_fence(__ATOMIC_RELEASE, "agent");
;             asm volatile("s_waitcnt vmcnt(0)" ::: "memory");
;             const unsigned og = xb_add(&bar[XB_TOP], 1u);
;             const unsigned tg = og / nx;
;             if (og + 1u == (tg + 1u) * nx) xb_add(&bar[XB_TOPGEN], 1u);
;             else XB_SPIN(xb_ld(&bar[XB_TOPGEN]) == tg, bar);
;             __builtin_amdgcn_fence(__ATOMIC_ACQUIRE, "agent");
;             xb_add(&bar[XB_XGEN(b.x)], 1u);
; __global__ void __launch_bounds__(512, 2) mega_fwd(Params p) {
;     ...
;     grid.sync();
.LBB0_60:
	s_mov_b64 exec, -1
	v_writelane_b32 v245, s0, 0
	v_writelane_b32 v245, s1, 1
	v_writelane_b32 v245, s2, 2
	v_writelane_b32 v245, s3, 3
	v_writelane_b32 v245, s4, 4
	v_writelane_b32 v245, s5, 5
	v_writelane_b32 v245, s6, 6
	v_writelane_b32 v245, s7, 7
	v_writelane_b32 v245, s8, 8
	v_writelane_b32 v245, s9, 9
	v_writelane_b32 v245, s10, 10
	v_writelane_b32 v245, s11, 11
	v_writelane_b32 v245, s12, 12
	v_writelane_b32 v245, s13, 13
	v_writelane_b32 v245, s14, 14
	v_writelane_b32 v245, s15, 15
	v_writelane_b32 v245, s16, 16
	v_writelane_b32 v245, s17, 17
	v_writelane_b32 v245, s18, 18
	v_writelane_b32 v245, s19, 19
	v_writelane_b32 v245, s20, 20
	v_writelane_b32 v245, s21, 21
	v_writelane_b32 v245, s22, 22
	v_writelane_b32 v245, s23, 23
	v_writelane_b32 v245, s24, 24
	v_writelane_b32 v245, s25, 25
	v_writelane_b32 v245, s26, 26
	v_writelane_b32 v245, s27, 27
	v_writelane_b32 v245, s28, 28
	v_writelane_b32 v245, s29, 29
	v_writelane_b32 v245, s30, 30
	v_writelane_b32 v245, s31, 31
	v_writelane_b32 v245, s32, 32
	v_writelane_b32 v245, s33, 33
	v_writelane_b32 v245, s34, 34
	v_writelane_b32 v245, s35, 35
	v_writelane_b32 v245, s36, 36
	v_writelane_b32 v245, s37, 37
	v_writelane_b32 v245, s38, 38
	v_writelane_b32 v245, s39, 39
	v_writelane_b32 v245, s40, 40
	v_writelane_b32 v245, s41, 41
	v_writelane_b32 v245, s42, 42
	v_writelane_b32 v245, s43, 43
	v_writelane_b32 v245, s44, 44
	v_writelane_b32 v245, s45, 45
	v_writelane_b32 v245, s46, 46
	v_writelane_b32 v245, s47, 47
	v_writelane_b32 v245, s48, 48
	v_writelane_b32 v245, s49, 49
	v_writelane_b32 v245, s50, 50
	v_writelane_b32 v245, s51, 51
	v_writelane_b32 v245, s52, 52
	v_writelane_b32 v245, s53, 53
	v_writelane_b32 v245, s54, 54
	v_writelane_b32 v245, s55, 55
	v_writelane_b32 v245, s56, 56
	v_writelane_b32 v245, s57, 57
	v_writelane_b32 v245, s58, 58
	v_writelane_b32 v245, s59, 59
	v_writelane_b32 v245, s60, 60
	v_writelane_b32 v245, s61, 61
	v_writelane_b32 v245, s62, 62
	v_writelane_b32 v245, s63, 63
	v_writelane_b32 v246, s64, 0
	v_writelane_b32 v246, s65, 1
	v_writelane_b32 v246, s66, 2
	v_writelane_b32 v246, s67, 3
	v_writelane_b32 v246, s68, 4
	v_writelane_b32 v246, s69, 5
	v_writelane_b32 v246, s70, 6
	v_writelane_b32 v246, s71, 7
	v_writelane_b32 v246, s72, 8
	v_writelane_b32 v246, s73, 9
	v_writelane_b32 v246, s74, 10
	v_writelane_b32 v246, s75, 11
	v_writelane_b32 v246, s76, 12
	v_writelane_b32 v246, s77, 13
	v_writelane_b32 v246, s78, 14
	v_writelane_b32 v246, s79, 15
	v_writelane_b32 v246, s80, 16
	v_writelane_b32 v246, s81, 17
	v_writelane_b32 v246, s82, 18
	v_writelane_b32 v246, s83, 19
	v_writelane_b32 v246, s84, 20
	v_writelane_b32 v246, s85, 21
	v_writelane_b32 v246, s86, 22
	v_writelane_b32 v246, s87, 23
	v_writelane_b32 v246, s88, 24
	v_writelane_b32 v246, s89, 25
	v_writelane_b32 v246, s90, 26
	v_writelane_b32 v246, s91, 27
	v_writelane_b32 v246, s92, 28
	v_writelane_b32 v246, s93, 29
	v_writelane_b32 v246, s94, 30
	v_writelane_b32 v246, s95, 31
	v_writelane_b32 v246, s96, 32
	v_writelane_b32 v246, s97, 33
	v_writelane_b32 v246, vcc_lo, 34
	v_writelane_b32 v246, vcc_hi, 35
	s_waitcnt vmcnt(0)
	v_cndmask_b32_e64 v0, 0, 1, s[2:3]
	v_cmp_ne_u32_e64 s[4:5], 1, v0
	s_andn2_b64 vcc, exec, s[2:3]
	s_waitcnt lgkmcnt(0)
	v_writelane_b32 v244, s4, 15
	s_barrier
	s_nop 0
	v_writelane_b32 v244, s5, 16
	s_cbranch_vccnz .Lgb0_141
	v_mbcnt_lo_u32_b32 v0, -1, 0
	v_mbcnt_hi_u32_b32 v0, -1, v0
	s_nop 0
	v_cmp_eq_u32_e32 vcc, 0, v0
	s_and_saveexec_b64 s[2:3], vcc
	s_cbranch_execz .Lgb0_140
	s_add_i32 s4, 0, 0x23fc0
	v_mov_b32_e32 v0, s4
	s_waitcnt vmcnt(0) expcnt(0) lgkmcnt(0)
	ds_read_b32 v2, v0
	s_add_i32 s4, 0, 0x23fc4
	v_mov_b32_e32 v0, s4
	ds_read_b32 v0, v0
	s_waitcnt lgkmcnt(1)
	v_cmp_ne_u32_e32 vcc, 0, v2
	s_cbranch_vccnz .Lgb0_104
	v_readlane_b32 s4, v244, 1
	s_mul_i32 s33, s95, s4
	s_add_u32 s4, s92, 0xc0200
	s_addc_u32 s5, s93, 0
	s_add_u32 s6, s92, 0xc0400
	s_addc_u32 s7, s93, 0
	s_add_u32 s10, s92, 0xc0500
	s_addc_u32 s11, s93, 0
	s_add_u32 s16, s92, 0xc0600
	s_addc_u32 s17, s93, 0
	s_add_u32 s20, s92, 0xc0700
	s_addc_u32 s21, s93, 0
	s_add_u32 s22, s92, 0xc0800
	s_addc_u32 s23, s93, 0
	s_add_u32 s24, s92, 0xc0900
	s_addc_u32 s25, s93, 0
	s_add_u32 s26, s92, 0xc0a00
	s_addc_u32 s27, s93, 0
	s_add_u32 s28, s92, 0xc0b00
	s_addc_u32 s29, s93, 0
	s_add_u32 s30, s92, 0xc0c00
	s_addc_u32 s31, s93, 0
	s_add_u32 s34, s92, 0xc0d00
	s_addc_u32 s35, s93, 0
	s_add_u32 s38, s92, 0xc0e00
	s_addc_u32 s39, s93, 0
	s_add_u32 s40, s92, 0xc0f00
	s_addc_u32 s41, s93, 0
	s_add_u32 s42, s92, 0xc1000
	s_addc_u32 s43, s93, 0
	s_add_u32 s44, s92, 0xc1100
	s_addc_u32 s45, s93, 0
	s_add_u32 s46, s92, 0xc1200
	s_addc_u32 s47, s93, 0
	s_add_u32 s48, s92, 0xc1300
	s_mul_i32 s33, s33, s94
	s_addc_u32 s49, s93, 0
	s_mov_b32 s72, 1
	v_mov_b32_e32 v16, 0
	s_branch .Lgb0_92

; #define LAS __attribute__((address_space(3)))
; #define BAR_LDS() do { asm volatile("s_waitcnt lgkmcnt(0)" ::: "memory"); __builtin_amdgcn_s_barrier(); asm volatile("" ::: "memory"); } while (0)
; #define lane (lane_now())
; __device__ __forceinline__ void norm_phase(const float* src, const float* g, const float* mod, int ish, int isc, bf16_t* dst, LAS unsigned char* lds, int gw, int ngw, int wave, int lane) {
;     LAS float* GSl = (LAS float*)lds; LAS float* SHl = GSl + 4096;
;     for (int i = wave * 64 + lane; i < 4096; i += 512) { const int b = i >> 10, c = i & 1023; GSl[i] = g[c] * (1.f + mod[(size_t)b * NMOD + isc * 1024 + c]); SHl[i] = mod[(size_t)b * NMOD + ish * 1024 + c]; }
;     BAR_LDS();
; __device__ __forceinline__ void xcd_barrier(const XcdBarrier& b) {
;     ...
;             asm volatile("s_waitcnt vmcnt(0)" ::: "memory");
;         }
;     }
;     __syncthreads();
; }
.Lgb0_141:
	s_mov_b64 exec, -1
	v_readlane_b32 s0, v245, 0
	v_readlane_b32 s1, v245, 1
	v_readlane_b32 s2, v245, 2
	v_readlane_b32 s3, v245, 3
	v_readlane_b32 s4, v245, 4
	v_readlane_b32 s5, v245, 5
	v_readlane_b32 s6, v245, 6
	v_readlane_b32 s7, v245, 7
	v_readlane_b32 s8, v245, 8
	v_readlane_b32 s9, v245, 9
	v_readlane_b32 s10, v245, 10
	v_readlane_b32 s11, v245, 11
	v_readlane_b32 s12, v245, 12
	v_readlane_b32 s13, v245, 13
	v_readlane_b32 s14, v245, 14
	v_readlane_b32 s15, v245, 15
	v_readlane_b32 s16, v245, 16
	v_readlane_b32 s17, v245, 17
	v_readlane_b32 s18, v245, 18
	v_readlane_b32 s19, v245, 19
	v_readlane_b32 s20, v245, 20
	v_readlane_b32 s21, v245, 21
	v_readlane_b32 s22, v245, 22
	v_readlane_b32 s23, v245, 23
	v_readlane_b32 s24, v245, 24
	v_readlane_b32 s25, v245, 25
	v_readlane_b32 s26, v245, 26
	v_readlane_b32 s27, v245, 27
	v_readlane_b32 s28, v245, 28
	v_readlane_b32 s29, v245, 29
	v_readlane_b32 s30, v245, 30
	v_readlane_b32 s31, v245, 31
	v_readlane_b32 s32, v245, 32
	v_readlane_b32 s33, v245, 33
	v_readlane_b32 s34, v245, 34
	v_readlane_b32 s35, v245, 35
	v_readlane_b32 s36, v245, 36
	v_readlane_b32 s37, v245, 37
	v_readlane_b32 s38, v245, 38
	v_readlane_b32 s39, v245, 39
	v_readlane_b32 s40, v245, 40
	v_readlane_b32 s41, v245, 41
	v_readlane_b32 s42, v245, 42
	v_readlane_b32 s43, v245, 43
	v_readlane_b32 s44, v245, 44
	v_readlane_b32 s45, v245, 45
	v_readlane_b32 s46, v245, 46
	v_readlane_b32 s47, v245, 47
	v_readlane_b32 s48, v245, 48
	v_readlane_b32 s49, v245, 49
	v_readlane_b32 s50, v245, 50
	v_readlane_b32 s51, v245, 51
	v_readlane_b32 s52, v245, 52
	v_readlane_b32 s53, v245, 53
	v_readlane_b32 s54, v245, 54
	v_readlane_b32 s55, v245, 55
	v_readlane_b32 s56, v245, 56
	v_readlane_b32 s57, v245, 57
	v_readlane_b32 s58, v245, 58
	v_readlane_b32 s59, v245, 59
	v_readlane_b32 s60, v245, 60
	v_readlane_b32 s61, v245, 61
	v_readlane_b32 s62, v245, 62
	v_readlane_b32 s63, v245, 63
	v_readlane_b32 s64, v246, 0
	v_readlane_b32 s65, v246, 1
	v_readlane_b32 s66, v246, 2
	v_readlane_b32 s67, v246, 3
	v_readlane_b32 s68, v246, 4
	v_readlane_b32 s69, v246, 5
	v_readlane_b32 s70, v246, 6
	v_readlane_b32 s71, v246, 7
	v_readlane_b32 s72, v246, 8
	v_readlane_b32 s73, v246, 9
	v_readlane_b32 s74, v246, 10
	v_readlane_b32 s75, v246, 11
	v_readlane_b32 s76, v246, 12
	v_readlane_b32 s77, v246, 13
	v_readlane_b32 s78, v246, 14
	v_readlane_b32 s79, v246, 15
	v_readlane_b32 s80, v246, 16
	v_readlane_b32 s81, v246, 17
	v_readlane_b32 s82, v246, 18
	v_readlane_b32 s83, v246, 19
	v_readlane_b32 s84, v246, 20
	v_readlane_b32 s85, v246, 21
	v_readlane_b32 s86, v246, 22
	v_readlane_b32 s87, v246, 23
	v_readlane_b32 s88, v246, 24
	v_readlane_b32 s89, v246, 25
	v_readlane_b32 s90, v246, 26
	v_readlane_b32 s91, v246, 27
	v_readlane_b32 s92, v246, 28
	v_readlane_b32 s93, v246, 29
	v_readlane_b32 s94, v246, 30
	v_readlane_b32 s95, v246, 31
	v_readlane_b32 s96, v246, 32
	v_readlane_b32 s97, v246, 33
	v_readlane_b32 vcc_lo, v246, 34
	v_readlane_b32 vcc_hi, v246, 35
	s_nop 7
	s_barrier
	v_mbcnt_lo_u32_b32 v0, -1, 0
	v_mbcnt_hi_u32_b32 v0, -1, v0
	s_movk_i32 s0, 0x1000
	v_add_u32_e32 v2, s86, v0
	v_cmp_gt_i32_e32 vcc, s0, v2
	s_and_saveexec_b64 s[6:7], vcc
	s_cbranch_execz .LBB0_84
	v_max_i32_e32 v1, 0xe00, v2
	v_sub_u32_e32 v1, v1, v2
	v_add_u32_e32 v3, 0x1ff, v1
	s_movk_i32 s0, 0xa00
	v_cmp_gt_u32_e64 s[10:11], s0, v3
	s_movk_i32 s0, 0x9ff
	v_cmp_lt_u32_e32 vcc, s0, v3
	s_and_saveexec_b64 s[16:17], vcc
	s_cbranch_execz .LBB0_81
	v_readlane_b32 s0, v244, 2
	v_lshrrev_b32_e32 v1, 9, v3
	s_and_b32 s0, s0, 0x3c0
	v_add_u16_e32 v4, s0, v0
	v_and_b32_e32 v5, 0x3ff, v1
	v_lshlrev_b16_e32 v6, 9, v1
	s_mov_b32 s4, 0x80000
	v_and_b32_e32 v4, 0x3ff, v4
	v_and_b32_e32 v6, 0x200, v6
	v_cmp_gt_u16_e32 vcc, 2, v5
	v_cmp_gt_u32_e64 s[4:5], s4, v3
	v_cmp_le_u16_e64 s[0:1], v6, v4
	s_and_b64 s[4:5], vcc, s[4:5]
	s_and_b64 s[20:21], s[4:5], s[0:1]
	s_mov_b64 s[4:5], -1
	s_and_saveexec_b64 s[0:1], s[20:21]
	s_cbranch_execz .LBB0_80
	v_add_u32_e32 v3, 0x200, v2
	v_add_u32_e32 v8, -1, v1
	v_cmp_lt_u32_e32 vcc, 1, v8
	v_mov_b32_e32 v6, 0
	v_mov_b64_e32 v[4:5], v[2:3]
	s_and_saveexec_b64 s[4:5], vcc
	s_cbranch_execz .LBB0_77
	v_lshrrev_b32_e32 v4, 1, v8
	s_lshl_b32 s20, s83, 8
	v_add_u32_e32 v4, 1, v4
	s_add_i32 s20, s20, 0
	v_and_b32_e32 v9, -2, v4
	s_mov_b32 s22, 0
	v_lshl_add_u32 v10, v0, 2, s20
	s_mov_b64 s[20:21], 0
	v_mov_b32_e32 v7, 0
	s_movk_i32 s23, 0x1000
	v_mov_b64_e32 v[4:5], v[2:3]

; #define BAR_LDS() do { asm volatile("s_waitcnt lgkmcnt(0)" ::: "memory"); __builtin_amdgcn_s_barrier(); asm volatile("" ::: "memory"); } while (0)
; __device__ __forceinline__ h16* chunk_base(const Params& p, int item) { return (h16*)(p.ws + WS_SC) + ((size_t)(item >> 7) * SEQ + (size_t)(item & 127) * 64) * 384; }
; #define lane (lane_now())
; __device__ __forceinline__ void chunk_load(const Params& p, int item, int tid, h16 (&raw)[48]) {
;     const h16* base = chunk_base(p, item) + (size_t)(8 * (tid >> 6)) * 384 + (tid & 63);
; #pragma unroll
;     for (int i = 0; i < 8; ++i)
; #pragma unroll
;         for (int vq = 0; vq < 6; ++vq) raw[i * 6 + vq] = base[(size_t)i * 384 + vq * 64];
; }
; __device__ __forceinline__ void chunk_pre(const Params& p, LAS unsigned char* lds, int item, int next_item, int tid, int wave, int lane, h16 (&raw)[48]) {
;     ...
;     const int fr = lane & 15, fq = lane >> 4;
;     {
;         const int g = tid >> 6, k = tid & 63;
;         float wv[8], lp[8];
; #pragma unroll
;         for (int i = 0; i < 8; ++i) wv[i] = (float)raw[i * 6 + 2];
;         lp[0] = wv[0];
; #pragma unroll
;         for (int i = 1; i < 8; ++i) lp[i] = lp[i - 1] * wv[i];
;         GT[g * 64 + k] = lp[7];
;         BAR_LDS();
;         float bs = 1.f, WL = 1.f;
; #pragma unroll
;         for (int q = 0; q < 8; ++q) { const float gq = GT[q * 64 + k]; if (q < g) bs *= gq; WL *= gq; }
; __global__ void __launch_bounds__(512, 2) mega_fwd(Params p) {
;     ...
;     { const int lane7 = lane, tid7 = wave * 64 + lane7;
;       h16 raw[48]; if ((int)blockIdx.x < 32 * 128) chunk_load(p, (int)blockIdx.x, tid7, raw);
;       for (int it = blockIdx.x; it < 32 * 128; it += G) chunk_pre(p, lds, it, (it + G < 32 * 128) ? it + G : -1, tid7, wave, lane7, raw); }
.LBB0_920:
	s_add_u32 s6, s92, 0x13b00000
	s_addc_u32 s7, s93, 0
	s_cmpk_lt_i32 s82, 0x1000
	s_movk_i32 s53, 0x1000
	s_waitcnt lgkmcnt(0)
	s_barrier
	v_mbcnt_lo_u32_b32 v1, -1, 0
	v_mbcnt_hi_u32_b32 v1, -1, v1
	s_cbranch_scc0 .LBB0_945
	v_readlane_b32 s45, v244, 0
	s_ashr_i32 s0, s45, 7
	s_ashr_i32 s1, s0, 31
	s_lshl_b32 s4, s45, 6
	s_lshl_b64 s[0:1], s[0:1], 13
	s_and_b32 s4, s4, 0x1fc0
	s_or_b32 s4, s0, s4
	s_mulk_i32 s1, 0x300
	s_mul_hi_u32 s5, s4, 0x300
	s_add_i32 s5, s5, s1
	s_mulk_i32 s4, 0x300
	v_add_u32_e32 v0, s86, v1
	s_add_u32 s4, s6, s4
	s_addc_u32 s5, s7, s5
	v_ashrrev_i32_e32 v2, 3, v0
	s_movk_i32 s0, 0x300
	s_waitcnt vmcnt(3)
	v_and_b32_e32 v4, -8, v2
	v_mov_b64_e32 v[2:3], s[4:5]
	v_and_b32_e32 v5, 63, v1
	v_mad_i64_i32 v[2:3], s[4:5], v4, s0, v[2:3]
	v_lshlrev_b32_e32 v20, 1, v5
	v_mov_b32_e32 v21, 0
	v_lshl_add_u64 v[2:3], v[2:3], 0, v[20:21]
	global_load_ushort v40, v[2:3], off
	global_load_ushort v41, v[2:3], off offset:128
	global_load_ushort v42, v[2:3], off offset:256
	global_load_ushort v43, v[2:3], off offset:384
	global_load_ushort v44, v[2:3], off offset:512
	global_load_ushort v45, v[2:3], off offset:640
	global_load_ushort v46, v[2:3], off offset:768
	global_load_ushort v47, v[2:3], off offset:896
	global_load_ushort v48, v[2:3], off offset:1024
	global_load_ushort v49, v[2:3], off offset:1152
	global_load_ushort v50, v[2:3], off offset:1280
	global_load_ushort v51, v[2:3], off offset:1408
	global_load_ushort v52, v[2:3], off offset:1536
	global_load_ushort v53, v[2:3], off offset:1664
	global_load_ushort v54, v[2:3], off offset:1792
	global_load_ushort v55, v[2:3], off offset:1920
	global_load_ushort v56, v[2:3], off offset:2048
	global_load_ushort v57, v[2:3], off offset:2176
	global_load_ushort v58, v[2:3], off offset:2304
	global_load_ushort v59, v[2:3], off offset:2432
	global_load_ushort v60, v[2:3], off offset:2560
	global_load_ushort v61, v[2:3], off offset:2688
	global_load_ushort v62, v[2:3], off offset:2816
	global_load_ushort v64, v[2:3], off offset:2944
	global_load_ushort v66, v[2:3], off offset:3072
	global_load_ushort v67, v[2:3], off offset:3200
	global_load_ushort v68, v[2:3], off offset:3328
	global_load_ushort v69, v[2:3], off offset:3456
	global_load_ushort v70, v[2:3], off offset:3584
	global_load_ushort v71, v[2:3], off offset:3712
	global_load_ushort v72, v[2:3], off offset:3840
	global_load_ushort v73, v[2:3], off offset:3968
	v_add_co_u32_e32 v2, vcc, s53, v2
	v_and_b32_e32 v6, 15, v1
	s_nop 0
	v_addc_co_u32_e32 v3, vcc, 0, v3, vcc
	global_load_ushort v75, v[2:3], off
	global_load_ushort v76, v[2:3], off offset:128
	global_load_ushort v78, v[2:3], off offset:256
	global_load_ushort v80, v[2:3], off offset:384
	global_load_ushort v81, v[2:3], off offset:512
	global_load_ushort v82, v[2:3], off offset:640
	global_load_ushort v83, v[2:3], off offset:768
	global_load_ushort v84, v[2:3], off offset:896
	global_load_ushort v85, v[2:3], off offset:1024
	global_load_ushort v86, v[2:3], off offset:1152
	global_load_ushort v87, v[2:3], off offset:1280
	global_load_ushort v88, v[2:3], off offset:1408
	global_load_ushort v89, v[2:3], off offset:1536
	global_load_ushort v90, v[2:3], off offset:1664
	global_load_ushort v92, v[2:3], off offset:1792
	global_load_ushort v93, v[2:3], off offset:1920
	v_ashrrev_i32_e32 v2, 6, v0
	v_cmp_lt_i32_e64 s[4:5], 1, v2
	v_cmp_eq_u32_e64 s[46:47], 0, v6
	v_cmp_lt_i32_e64 s[82:83], 0, v2
	v_writelane_b32 v244, s4, 33
	v_cndmask_b32_e64 v101, 0, 1.0, s[46:47]
	v_cmp_eq_u32_e64 s[46:47], 1, v6
	v_writelane_b32 v244, s5, 34
	v_cmp_lt_i32_e64 s[4:5], 2, v2
	v_cndmask_b32_e64 v103, 0, 1.0, s[46:47]
	v_cmp_eq_u32_e64 s[46:47], 2, v6
	v_writelane_b32 v244, s4, 35
	s_add_i32 s8, 0, 0x1a800
	v_cndmask_b32_e64 v104, 0, 1.0, s[46:47]
	v_writelane_b32 v244, s5, 36
	v_cmp_lt_i32_e64 s[4:5], 3, v2
	v_cmp_eq_u32_e64 s[46:47], 3, v6
	v_ashrrev_i32_e32 v7, 4, v1
	v_writelane_b32 v244, s4, 37
	v_cndmask_b32_e64 v105, 0, 1.0, s[46:47]
	v_cmp_eq_u32_e64 s[46:47], 4, v6
	v_writelane_b32 v244, s5, 38
	v_cmp_lt_i32_e64 s[4:5], 4, v2
	v_cndmask_b32_e64 v106, 0, 1.0, s[46:47]
	v_cmp_eq_u32_e64 s[46:47], 5, v6
	v_writelane_b32 v244, s4, 39
	s_movk_i32 s79, 0x90
	v_cndmask_b32_e64 v107, 0, 1.0, s[46:47]
	v_writelane_b32 v244, s5, 40
	v_cmp_lt_i32_e64 s[4:5], 5, v2
	v_cmp_eq_u32_e64 s[46:47], 6, v6
	s_waitcnt vmcnt(50)
	v_mov_b32_e32 v10, 0x900
	v_writelane_b32 v244, s4, 41
	v_cndmask_b32_e64 v108, 0, 1.0, s[46:47]
	v_cmp_eq_u32_e64 s[46:47], 7, v6
	v_writelane_b32 v244, s5, 42
	v_cmp_lt_i32_e64 s[4:5], 6, v2
	v_cndmask_b32_e64 v109, 0, 1.0, s[46:47]
	v_cmp_eq_u32_e64 s[46:47], 8, v6
	v_writelane_b32 v244, s4, 43
	v_lshlrev_b32_e32 v100, 1, v6
	v_cndmask_b32_e64 v110, 0, 1.0, s[46:47]
	v_writelane_b32 v244, s5, 44
	v_cmp_lt_i32_e64 s[4:5], 7, v2
	v_cmp_eq_u32_e64 s[46:47], 9, v6
	s_add_i32 s1, 0, 0x22800
	v_writelane_b32 v244, s4, 45
	v_cndmask_b32_e64 v111, 0, 1.0, s[46:47]
	v_cmp_eq_u32_e64 s[46:47], 10, v6
	v_writelane_b32 v244, s5, 46
	s_movk_i32 s4, 0x240
	v_mul_lo_u32 v3, v2, s4
	v_or_b32_e32 v3, v3, v5
	v_lshl_add_u32 v74, v3, 1, 0
	v_mul_u32_u24_e32 v3, 0x48, v5
	v_lshlrev_b32_e32 v3, 1, v3
	v_lshlrev_b32_e32 v2, 4, v2
	v_add3_u32 v77, 0, v3, v2
	v_add3_u32 v79, s8, v3, v2
	v_mov_b64_e32 v[2:3], s[6:7]
	v_mad_i64_i32 v[2:3], s[4:5], v4, s0, v[2:3]
	v_readlane_b32 s4, v244, 14
	s_lshl_b32 s4, s4, 3
	s_and_b32 s4, s4, 0x1ffffff0
	v_or_b32_e32 v4, s4, v6
	v_readlane_b32 s4, v244, 20
	v_cndmask_b32_e64 v112, 0, 1.0, s[46:47]
	v_cmp_eq_u32_e64 s[46:47], 11, v6
	v_lshl_add_u64 v[22:23], v[2:3], 0, v[20:21]
	s_and_b32 s4, s4, 32
	v_and_b32_e32 v20, -16, v0
	v_cndmask_b32_e64 v113, 0, 1.0, s[46:47]
	v_cmp_eq_u32_e64 s[46:47], 12, v6
	v_mul_lo_u32 v2, v4, s79
	v_or_b32_e32 v3, s4, v6
	v_lshl_add_u32 v24, v7, 2, s4
	s_add_i32 s5, 0, 0x12000
	v_lshlrev_b32_e32 v25, 2, v20
	v_lshlrev_b32_e32 v26, 1, v20
	v_mul_lo_u32 v38, v20, s79
	v_lshlrev_b32_e32 v20, 8, v20
	v_cndmask_b32_e64 v114, 0, 1.0, s[46:47]
	v_cmp_eq_u32_e64 s[46:47], 13, v6
	v_mul_u32_u24_e32 v9, 0x90, v3
	v_mad_u32_u24 v10, v3, s79, v10
	v_lshlrev_b32_e32 v3, 8, v4
	s_add_i32 s18, 0, 0x16800
	s_waitcnt vmcnt(49)
; #define LAS __attribute__((address_space(3)))
; __device__ __forceinline__ void chunk_pre(const Params& p, LAS unsigned char* lds, int item, int next_item, int tid, int wave, int lane, h16 (&raw)[48]) {
;     ...
;     const int fr = lane & 15, fq = lane >> 4;
;     {
;         const int g = tid >> 6, k = tid & 63;
;         float wv[8], lp[8];
; #pragma unroll
;         for (int i = 0; i < 8; ++i) wv[i] = (float)raw[i * 6 + 2];
;         lp[0] = wv[0];
; #pragma unroll
;         for (int i = 1; i < 8; ++i) lp[i] = lp[i - 1] * wv[i];
;         GT[g * 64 + k] = lp[7];
;         BAR_LDS();
;         float bs = 1.f, WL = 1.f;
; #pragma unroll
;         for (int q = 0; q < 8; ++q) { const float gq = GT[q * 64 + k]; if (q < g) bs *= gq; WL *= gq; }
;         float bhv[8], khv[8], vtv[8], atv[8];
; #pragma unroll
;         for (int i = 0; i < 8; ++i) {
;             const int t = 8 * g + i;
;             const float kk = (float)raw[i * 6 + 0], wr = (float)raw[i * 6 + 1], bb = (float)raw[i * 6 + 3], kx = (float)raw[i * 6 + 4], vv = (float)raw[i * 6 + 5];
;             const float Wt = bs * lp[i], Wp = (i == 0) ? bs : bs * lp[i - 1], iW = 1.f / Wt;
;             atv[i] = -kk * Wp; At[t * MS + k] = (bf16_t)(pk2(-kk * Wp, 0.f) & 0xffffu); Rt[t * MS + k] = (bf16_t)(pk2(wr * Wp, 0.f) & 0xffffu);
;             Bt[t * MS + k] = (bf16_t)(pk2(bb * iW, 0.f) & 0xffffu); Kt[t * MS + k] = (bf16_t)(pk2(kx * iW, 0.f) & 0xffffu);
;             bhv[i] = bb * iW * WL; khv[i] = kx * iW * WL; vtv[i] = vv;
;         }
;         *(LAS u32x4*)(BhT + k * MS + 8 * g) = (u32x4){pk2(bhv[0], bhv[1]), pk2(bhv[2], bhv[3]), pk2(bhv[4], bhv[5]), pk2(bhv[6], bhv[7])};
;         *(LAS u32x4*)(KhT + k * MS + 8 * g) = (u32x4){pk2(khv[0], khv[1]), pk2(khv[2], khv[3]), pk2(khv[4], khv[5]), pk2(khv[6], khv[7])};
;         *(LAS u32x4*)(VT + k * MS + 8 * g) = (u32x4){pk2(vtv[0], vtv[1]), pk2(vtv[2], vtv[3]), pk2(vtv[4], vtv[5]), pk2(vtv[6], vtv[7])};
;         *(LAS u32x4*)(AtT + k * MS + 8 * g) = (u32x4){pk2(atv[0], atv[1]), pk2(atv[2], atv[3]), pk2(atv[4], atv[5]), pk2(atv[6], atv[7])};
;     }
;     if (next_item >= 0) chunk_load(p, next_item, tid, raw);
;     BAR_LDS();
;     const int a0 = 16 * (wave >> 1), ar = a0 + fr;
;     {
;         f32x4 acc[2];
; #pragma unroll
;         for (int which = 0; which < 4; ++which) {
;             acc[0] = (f32x4){0.f, 0.f, 0.f, 0.f}; acc[1] = acc[0];
	v_lshlrev_b32_e32 v15, 2, v24
	s_waitcnt vmcnt(48)
	v_add_u32_e32 v19, s5, v2
	s_add_i32 s5, 0, 0x14400
	v_add3_u32 v36, 0, v26, v100
	v_lshlrev_b32_e32 v26, 6, v0
	v_or_b32_e32 v39, 0x100, v20
	v_or_b32_e32 v144, 0x200, v20
	v_or_b32_e32 v145, 0x300, v20
	v_or_b32_e32 v146, 0x400, v20
	v_or_b32_e32 v147, 0x500, v20
	v_or_b32_e32 v148, 0x600, v20
	v_or_b32_e32 v149, 0x700, v20
	v_or_b32_e32 v150, 0x800, v20
	v_or_b32_e32 v151, 0x900, v20
	v_or_b32_e32 v152, 0xa00, v20
	v_or_b32_e32 v153, 0xb00, v20
	v_or_b32_e32 v154, 0xc00, v20
	v_or_b32_e32 v155, 0xd00, v20
	v_cndmask_b32_e64 v115, 0, 1.0, s[46:47]
	v_or_b32_e32 v156, 0xe00, v20
	v_cmp_eq_u32_e64 s[46:47], 14, v6
	v_or_b32_e32 v20, 15, v0
	v_lshl_add_u32 v65, v5, 2, s1
	v_lshlrev_b32_e32 v5, 3, v7
	v_add_u32_e32 v7, 0, v2
	v_add3_u32 v94, s18, v3, v15
	v_lshlrev_b32_e32 v3, 1, v24
	v_add_u32_e32 v28, s5, v2
	s_add_i32 s5, 0, 0x1cc00
	v_lshlrev_b32_e32 v98, 2, v6
	v_and_b32_e32 v37, 0xfffffc00, v26
	v_cndmask_b32_e64 v116, 0, 1.0, s[46:47]
	v_lshlrev_b32_e32 v157, 8, v20
	v_cmp_eq_u32_e64 s[46:47], 15, v6
	v_mul_lo_u32 v6, v20, s79
	v_ashrrev_i32_e32 v20, 8, v0
	v_ashrrev_i32_e32 v26, 4, v0
	v_add_u32_e32 v95, v7, v3
	v_add_u32_e32 v96, v19, v3
	v_add_u32_e32 v97, v28, v3
	v_add_u32_e32 v3, s5, v2
	s_movk_i32 s5, 0x600
	v_and_b32_e32 v27, 15, v26
	v_add_u32_e32 v29, 2, v20
	v_cmp_gt_i32_e64 s[10:11], s5, v0
	v_lshl_or_b32 v30, v29, 4, v27
	v_lshl_add_u32 v31, v30, 8, s18
	v_writelane_b32 v244, s10, 47
	v_lshlrev_b32_e32 v32, 6, v20
	v_cvt_pk_bf16_f32 v102, v101, s0
	v_writelane_b32 v244, s11, 48
	v_cmp_gt_i32_e64 s[10:11], 64, v0
	v_cndmask_b32_e64 v117, 0, 1.0, s[46:47]
	v_cmp_gt_i32_e64 s[46:47], s0, v0
	s_add_i32 s42, 0, 0x21800
	v_add_u32_e32 v119, v31, v32
	v_and_b32_e32 v31, 0x3fffff00, v0
	s_add_i32 s43, 0, 0x20000
	s_add_i32 s0, 0, 0x20c00
	v_lshlrev_b32_e32 v8, 2, v0
	v_writelane_b32 v244, s10, 49
	v_add_u32_e32 v118, s42, v98
	v_lshlrev_b32_e32 v31, 2, v31
	v_add_u32_e32 v121, s43, v98
	v_add_u32_e32 v128, s0, v98
	s_add_i32 s0, 0, 0x1fc00
	v_add_u32_e32 v63, s1, v8
	v_writelane_b32 v244, s11, 50
	s_add_i32 s19, 0, 0x1f000
	v_add_u32_e32 v122, v121, v31
	v_lshlrev_b32_e32 v27, 6, v27
	v_add_u32_e32 v123, v118, v31
	v_lshlrev_b32_e32 v29, 10, v29
	v_add_u32_e32 v130, s0, v25
	v_lshl_add_u32 v136, v4, 2, s1
	v_cmp_eq_u32_e64 s[0:1], v24, v4
	v_and_b32_e32 v1, -16, v1
	v_or_b32_e32 v12, 1, v24
	v_add_u32_e32 v124, v123, v27
	v_add3_u32 v125, s19, v29, v27
	v_add_u32_e32 v126, v122, v27
	v_mul_lo_u32 v27, v30, s79
	v_writelane_b32 v244, s0, 51
	v_add_u32_e32 v91, v7, v1
	v_add_u32_e32 v11, 0, v1
	v_add_u32_e32 v27, 0, v27
	v_lshlrev_b32_e32 v20, 5, v20
	v_add3_u32 v132, s8, v2, v1
	v_add_u32_e32 v133, v3, v1
	v_add_u32_e32 v134, v19, v1
	v_mul_lo_u32 v2, v4, 6
	v_add_u32_e32 v135, v28, v1
	v_writelane_b32 v244, s1, 52
	v_cmp_eq_u32_e64 s[0:1], v12, v4
	v_max_i32_e32 v1, 0x400, v0
	v_or_b32_e32 v13, 2, v24
	s_lshl_b32 s4, s4, 1
	v_add3_u32 v127, v27, v20, v100
	v_add_u32_e32 v20, 2, v2
	v_writelane_b32 v244, s0, 53
	v_sub_u32_e32 v1, v1, v0
	v_add_u32_e32 v34, s4, v3
	v_add_u32_e32 v99, s19, v98
	v_lshlrev_b32_e32 v162, 8, v26
	v_add_u32_e32 v129, s42, v8
	v_mul_lo_u32 v8, v26, s79
	v_lshlrev_b64 v[26:27], 7, v[20:21]
	v_add_u32_e32 v20, 3, v2
	v_mov_b32_e32 v3, v21
	v_writelane_b32 v244, s1, 54
	v_cmp_eq_u32_e64 s[0:1], v13, v4
	v_add_u32_e32 v1, 0x1ff, v1
	v_or_b32_e32 v14, 3, v24
	v_add_u32_e32 v15, 16, v24
	v_add_u32_e32 v16, 17, v24
	v_add_u32_e32 v17, 18, v24
	v_add_u32_e32 v18, 19, v24
	s_movk_i32 s5, 0x100
	v_add_u32_e32 v120, v99, v31
	v_lshlrev_b64 v[28:29], 7, v[20:21]
	v_lshlrev_b64 v[30:31], 7, v[2:3]
	v_writelane_b32 v244, s0, 55
	v_or_b32_e32 v20, 1, v2
	v_lshrrev_b32_e32 v2, 9, v1
	s_movk_i32 s8, 0x5ff
	v_cmp_lt_i32_e64 s[20:21], v24, v4
	v_cmp_lt_i32_e32 vcc, v12, v4
	v_cmp_lt_i32_e64 s[70:71], v13, v4
	v_cmp_lt_i32_e64 s[22:23], v14, v4
	v_cmp_lt_i32_e64 s[24:25], v15, v4
	v_cmp_lt_i32_e64 s[76:77], v16, v4
	v_cmp_lt_i32_e64 s[74:75], v17, v4
	v_cmp_lt_i32_e64 s[26:27], v18, v4
	v_cmp_gt_i32_e64 s[28:29], v24, v4
	v_cmp_gt_i32_e64 s[30:31], v13, v4
	v_cmp_gt_i32_e64 s[34:35], v14, v4
	v_cmp_gt_i32_e64 s[36:37], v15, v4
	v_cmp_gt_i32_e64 s[38:39], v17, v4
	v_cmp_gt_i32_e64 s[40:41], v18, v4
	v_cmp_gt_i32_e64 s[48:49], s5, v0
	v_add_u32_e32 v7, s4, v7
	v_writelane_b32 v244, s1, 56
	v_cmp_eq_u32_e64 s[56:57], v14, v4
	v_cmp_eq_u32_e64 s[88:89], v15, v4
	v_cmp_eq_u32_e64 s[4:5], v16, v4
	v_cmp_eq_u32_e64 s[0:1], v17, v4
	v_cmp_eq_u32_e64 s[68:69], v18, v4
	v_add_u32_e32 v4, 1, v2
	v_cmp_lt_u32_e64 s[10:11], s8, v1
	v_and_b32_e32 v137, 0xfffffc, v4
	v_add_u32_e32 v35, s18, v25
	v_writelane_b32 v244, s10, 57
	s_or_b64 s[70:71], s[22:23], s[70:71]
	s_or_b64 s[74:75], s[26:27], s[74:75]
	v_writelane_b32 v244, s11, 58
	v_cmp_ne_u32_e64 s[10:11], v4, v137
	s_mov_b32 s9, 0
	v_add3_u32 v131, 0, v8, v100
	v_ashrrev_i32_e32 v25, 31, v24
	v_lshlrev_b64 v[32:33], 7, v[20:21]
	v_lshl_add_u32 v138, v137, 9, v0
	v_add_u32_e32 v3, 0x600, v0
	v_add_u32_e32 v2, 0x400, v0
	v_add_u32_e32 v1, 0x200, v0
	v_writelane_b32 v244, s10, 59
	v_add_u32_e32 v139, v11, v10
	v_add_u32_e32 v140, v34, v5
	v_add_u32_e32 v141, v99, v37
	v_add_u32_e32 v142, v36, v38
	v_add_u32_e32 v143, v35, v39
	v_add_u32_e32 v144, v35, v144
	v_add_u32_e32 v145, v35, v145
	v_add_u32_e32 v146, v35, v146
	v_add_u32_e32 v147, v35, v147
	v_add_u32_e32 v148, v35, v148
	v_add_u32_e32 v149, v35, v149
	v_add_u32_e32 v150, v35, v150
	v_add_u32_e32 v151, v35, v151
	v_add_u32_e32 v152, v35, v152
	v_add_u32_e32 v153, v35, v153
	v_add_u32_e32 v154, v35, v154
	v_add_u32_e32 v155, v35, v155
	v_add_u32_e32 v156, v35, v156
	v_add_u32_e32 v157, v35, v157
	v_add_u32_e32 v158, v36, v6
	s_movk_i32 s44, 0xff
	v_add_u32_e32 v159, v7, v5
	v_mov_b32_e32 v160, 0x300
	v_add_u32_e32 v161, v11, v9
	s_or_b64 s[72:73], s[70:71], vcc
	s_or_b64 s[76:77], s[74:75], s[76:77]
	v_add_u32_e32 v162, s18, v162
	v_writelane_b32 v244, s11, 60
	s_mov_b64 s[100:101], vcc
	v_cmp_gt_u32_e32 vcc, 0xc0, v0
	s_mov_b64 s[98:99], vcc
	v_lshrrev_b32_e32 v213, 1, v0
	v_and_b32_e32 v212, 1, v0
	v_lshrrev_b32_e32 v216, 4, v213
	v_and_b32_e32 v213, 15, v213
	v_cmp_lt_u32_e32 vcc, 2, v216
	s_nop 1
	v_cndmask_b32_e64 v217, 0, 1, vcc
	v_cmp_lt_u32_e32 vcc, 4, v216
	s_nop 1
	v_cndmask_b32_e64 v218, 0, 1, vcc
	v_add_u32_e32 v219, v217, v218
	v_lshl_add_u32 v213, v219, 4, v213
	v_add_u32_e32 v216, 1, v216
	v_lshlrev_b32_e32 v217, 1, v217
	v_sub_u32_e32 v216, v216, v217
	v_sub_u32_e32 v216, v216, v218
	v_lshlrev_b32_e32 v216, 5, v216
	v_lshl_add_u32 v212, v212, 4, v216
	v_mov_b32_e32 v217, 0x90
	v_mad_u32_u24 v212, v213, v217, v212
	v_mov_b32_e32 v214, 0
	v_mov_b32_e32 v215, 0
	s_mov_b64 vcc, s[100:101]
	s_branch .LBB0_923
; #define LAS __attribute__((address_space(3)))
; #define BAR_LDS() do { asm volatile("s_waitcnt lgkmcnt(0)" ::: "memory"); __builtin_amdgcn_s_barrier(); asm volatile("" ::: "memory"); } while (0)
; __device__ __forceinline__ unsigned pk2(float lo, float hi) { const f32x2c v = {lo, hi}; const bf16x2c b = __builtin_convertvector(v, bf16x2c); return __builtin_bit_cast(unsigned, b); }
; __device__ __forceinline__ float bflo(unsigned w) { return __uint_as_float(w << 16); }
; __device__ __forceinline__ float bfhi(unsigned w) { return __uint_as_float(w & 0xffff0000u); }
; __device__ __forceinline__ void chunk_pre(const Params& p, LAS unsigned char* lds, int item, int next_item, int tid, int wave, int lane, h16 (&raw)[48]) {
;     ...
;     {
;         f32x4 acc[2];
;         acc[0] = (f32x4){0.f, 0.f, 0.f, 0.f}; acc[1] = acc[0]; mm64(Tb, AtT, acc, wave, fr, fq);
; #pragma unroll
;         for (int nt = 0; nt < 2; ++nt) st_bf4(AbT + ar * MS + 32 * (wave & 1) + 16 * nt + 4 * fq, acc[nt]);
;         acc[0] = (f32x4){0.f, 0.f, 0.f, 0.f}; acc[1] = acc[0]; mm64(Tb, RH2T, acc, wave, fr, fq);
; #pragma unroll
;         for (int nt = 0; nt < 2; ++nt) st_bf4(P1T + ar * MS + 32 * (wave & 1) + 16 * nt + 4 * fq, acc[nt]);
;     }
;     BAR_LDS();
;     {
;         f32x4 acc[2];
;         acc[0] = (f32x4){0.f, 0.f, 0.f, 0.f}; acc[1] = acc[0];
;         mm64(AbT, Mrb, acc, wave, fr, fq);
; #pragma unroll
;         for (int nt = 0; nt < 2; ++nt) { const int b0 = 32 * (wave & 1) + 16 * nt + 4 * fq; const u32x2 rw = *(const LAS u32x2*)(Rt + ar * MS + b0);
;             const f32x4 v = acc[nt] + (f32x4){bflo(rw.x), bfhi(rw.x), bflo(rw.y), bfhi(rw.y)};
;             u32x2 w; w.x = pk2(v.x, v.y); w.y = pk2(v.z, v.w); *(u32x2*)(base + (size_t)(ar * 6 + 2) * 64 + b0) = w; }
;         acc[0] = (f32x4){0.f, 0.f, 0.f, 0.f}; acc[1] = acc[0];
;         mm64(P1T, Mrb, acc, wave, fr, fq); mm64(VT, Mrk, acc, wave, fr, fq);
; #pragma unroll
;         for (int nt = 0; nt < 2; ++nt) { const int b0 = 32 * (wave & 1) + 16 * nt + 4 * fq; *(f32x4*)((float*)(base + (size_t)(ar * 6 + 3) * 64) + b0) = acc[nt]; }
;         acc[0] = (f32x4){0.f, 0.f, 0.f, 0.f}; acc[1] = acc[0];
;         mm64(AbT, BhT, acc, wave, fr, fq);
;         { float WL = 1.f;
; #pragma unroll
;           for (int q = 0; q < 8; ++q) WL *= GT[q * 64 + ar];
.LBB0_922:
	s_or_b64 exec, exec, s[12:13]
	s_waitcnt lgkmcnt(0)
	s_barrier
	ds_read_b128 v[4:7], v132
	ds_read_b128 v[8:11], v161
	ds_read_b128 v[12:15], v161 offset:2304
	ds_read_b128 v[220:223], v132 offset:64
	ds_read_b128 v[16:19], v161 offset:64
	ds_read_b128 v[224:227], v161 offset:2368
	s_ashr_i32 s12, s45, 7
	s_waitcnt lgkmcnt(4)
	v_mfma_f32_16x16x32_bf16 v[8:11], v[8:11], v[4:7], 0
	v_add_u32_e32 v20, 0x6800, v95
	s_ashr_i32 s13, s12, 31
	s_lshl_b32 s8, s45, 6
	s_waitcnt lgkmcnt(3)
	v_mfma_f32_16x16x32_bf16 v[4:7], v[12:15], v[4:7], 0
	s_nop 0
	s_nop 0
	s_lshl_b64 s[12:13], s[12:13], 13
	s_and_b32 s8, s8, 0x1fc0
	s_waitcnt lgkmcnt(1)
	v_mfma_f32_16x16x32_bf16 v[8:11], v[16:19], v[220:223], v[8:11]
	s_nop 0
	s_or_b32 s8, s12, s8
	s_mul_i32 s12, s13, 0x300
	s_nop 4
	v_cvt_pk_bf16_f32 v8, v8, v9
	s_waitcnt lgkmcnt(0)
	v_mfma_f32_16x16x32_bf16 v[4:7], v[224:227], v[220:223], v[4:7]
	v_cvt_pk_bf16_f32 v9, v10, v11
	s_mul_hi_u32 s13, s8, 0x300
	s_add_i32 s13, s13, s12
	s_nop 4
	v_cvt_pk_bf16_f32 v4, v4, v5
	v_cvt_pk_bf16_f32 v5, v6, v7
	v_add_u32_e32 v6, 0x2000, v159
	ds_write2_b64 v6, v[8:9], v[4:5] offset0:128 offset1:132
	ds_read_b128 v[4:7], v133
	ds_read_b128 v[8:11], v161
	ds_read_b128 v[12:15], v161 offset:2304
	s_waitcnt lgkmcnt(1)
	v_mfma_f32_16x16x32_bf16 v[8:11], v[8:11], v[4:7], 0
	s_mulk_i32 s8, 0x300
	s_add_u32 s80, s6, s8
	s_addc_u32 s81, s7, s13
	s_waitcnt lgkmcnt(0)
	v_mfma_f32_16x16x32_bf16 v[4:7], v[12:15], v[4:7], 0
	ds_read_b128 v[12:15], v133 offset:64
	ds_read_b128 v[16:19], v161 offset:64
	v_lshl_add_u64 v[180:181], s[80:81], 0, v[26:27]
	v_readlane_b32 s12, v244, 51
	s_waitcnt lgkmcnt(0)
	v_mfma_f32_16x16x32_bf16 v[8:11], v[16:19], v[12:15], v[8:11]
	ds_read_b128 v[16:19], v161 offset:2368
	v_readlane_b32 s13, v244, 52
	s_and_b64 vcc, exec, s[10:11]
	s_waitcnt lgkmcnt(0)
	v_mfma_f32_16x16x32_bf16 v[4:7], v[16:19], v[12:15], v[4:7]
	s_nop 2
	v_cvt_pk_bf16_f32 v8, v8, v9
	v_cvt_pk_bf16_f32 v9, v10, v11
	s_mov_b32 s45, s50
	s_nop 1
	v_cvt_pk_bf16_f32 v4, v4, v5
	v_cvt_pk_bf16_f32 v5, v6, v7
	v_add_u32_e32 v6, 0x4800, v159
	ds_write2_b64 v6, v[8:9], v[4:5] offset1:4
	s_waitcnt lgkmcnt(0)
	s_barrier
	ds_read_b128 v[36:39], v134
	ds_read_b128 v[8:11], v161 offset:9216
	ds_read_b128 v[16:19], v161 offset:11520
	ds_read_b128 v[168:171], v134 offset:64
	ds_read_b128 v[4:7], v161 offset:9280
	ds_read2_b64 v[176:179], v20 offset0:128 offset1:132
	ds_read_b128 v[220:223], v161 offset:11584
	ds_read_b128 v[224:227], v161 offset:18432
	ds_read_b128 v[228:231], v161 offset:20736
	ds_read_b128 v[232:235], v161 offset:18496
	ds_read_b128 v[236:239], v161 offset:20800
	ds_read_b128 v[240:243], v135
	s_waitcnt lgkmcnt(10)
	v_mfma_f32_16x16x32_bf16 v[12:15], v[8:11], v[36:39], 0
	s_nop 0
	s_waitcnt lgkmcnt(6)
	v_lshlrev_b32_e32 v34, 16, v176
	v_mfma_f32_16x16x32_bf16 v[172:175], v[4:7], v[168:171], v[12:15]
	v_and_b32_e32 v35, 0xffff0000, v176
	v_lshlrev_b32_e32 v176, 16, v177
	v_and_b32_e32 v177, 0xffff0000, v177
	s_nop 0
	s_nop 0
	v_mfma_f32_16x16x32_bf16 v[164:167], v[16:19], v[36:39], 0
	s_nop 1
	v_add_f32_e64 v34, v172, v34
	v_add_f32_e64 v35, v173, v35
	v_pk_add_f32 v[174:175], v[174:175], v[176:177]
	v_cvt_pk_bf16_f32 v172, v34, v35
	s_waitcnt lgkmcnt(5)
	v_mfma_f32_16x16x32_bf16 v[164:167], v[220:223], v[168:171], v[164:167]
	v_lshlrev_b64 v[34:35], 1, v[24:25]
	v_cvt_pk_bf16_f32 v173, v174, v175
	v_lshl_add_u64 v[174:175], v[180:181], 0, v[34:35]
	global_store_dwordx2 v[174:175], v[172:173], off
	v_lshlrev_b32_e32 v172, 16, v178
	v_and_b32_e32 v173, 0xffff0000, v178
	v_lshlrev_b32_e32 v176, 16, v179
	v_and_b32_e32 v177, 0xffff0000, v179
	v_pk_add_f32 v[166:167], v[166:167], v[176:177]
	v_pk_add_f32 v[164:165], v[164:165], v[172:173]
	s_nop 0
	v_cvt_pk_bf16_f32 v164, v164, v165
	v_cvt_pk_bf16_f32 v165, v166, v167
	global_store_dwordx2 v[174:175], v[164:165], off offset:32
	s_nop 0
	s_nop 0
	s_waitcnt lgkmcnt(4)
	v_mfma_f32_16x16x32_bf16 v[164:167], v[224:227], v[36:39], 0
	s_waitcnt lgkmcnt(3)
	v_mfma_f32_16x16x32_bf16 v[36:39], v[228:231], v[36:39], 0
	s_nop 0
	s_waitcnt lgkmcnt(2)
	v_mfma_f32_16x16x32_bf16 v[164:167], v[232:235], v[168:171], v[164:167]
	s_nop 0
	s_waitcnt lgkmcnt(1)
	v_mfma_f32_16x16x32_bf16 v[36:39], v[236:239], v[168:171], v[36:39]
	ds_read_b128 v[172:175], v161 offset:55296
	ds_read_b128 v[224:227], v161 offset:57600
	s_nop 0
	s_nop 0
	s_waitcnt lgkmcnt(1)
	v_mfma_f32_16x16x32_bf16 v[164:167], v[172:175], v[240:243], v[164:167]
	s_nop 0
	s_waitcnt lgkmcnt(0)
	v_mfma_f32_16x16x32_bf16 v[36:39], v[224:227], v[240:243], v[36:39]
	ds_read_b128 v[168:171], v135 offset:64
	ds_read_b128 v[172:175], v161 offset:55360
	s_waitcnt lgkmcnt(0)
	v_mfma_f32_16x16x32_bf16 v[164:167], v[172:175], v[168:171], v[164:167]
	ds_read_b128 v[172:175], v161 offset:57664
	ds_read_b128 v[224:227], v91 offset:36864
	s_waitcnt lgkmcnt(1)
	v_mfma_f32_16x16x32_bf16 v[36:39], v[172:175], v[168:171], v[36:39]
	v_lshl_add_u64 v[168:169], s[80:81], 0, v[28:29]
	v_lshl_add_u64 v[168:169], v[24:25], 2, v[168:169]
	s_nop 2
	global_store_dwordx4 v[168:169], v[164:167], off
	s_nop 1
	global_store_dwordx4 v[168:169], v[36:39], off offset:64
	s_nop 0
	s_waitcnt lgkmcnt(0)
	v_mfma_f32_16x16x32_bf16 v[8:11], v[8:11], v[224:227], 0
	v_mfma_f32_16x16x32_bf16 v[16:19], v[16:19], v[224:227], 0
	ds_read_b128 v[36:39], v91 offset:36928
	ds_read2st64_b32 v[224:225], v136 offset1:1
	ds_read2st64_b32 v[226:227], v136 offset0:2 offset1:3
	ds_read2st64_b32 v[228:229], v136 offset0:4 offset1:5
	ds_read2st64_b32 v[230:231], v136 offset0:6 offset1:7
	ds_read_b128 v[232:235], v91 offset:18432
	ds_read_b128 v[236:239], v161 offset:36864
	ds_read_b128 v[240:243], v161 offset:39168
	s_waitcnt lgkmcnt(7)
; #define BAR_LDS() do { asm volatile("s_waitcnt lgkmcnt(0)" ::: "memory"); __builtin_amdgcn_s_barrier(); asm volatile("" ::: "memory"); } while (0)
; __device__ __forceinline__ unsigned pk2(float lo, float hi) { const f32x2c v = {lo, hi}; const bf16x2c b = __builtin_convertvector(v, bf16x2c); return __builtin_bit_cast(unsigned, b); }
; __device__ __forceinline__ void chunk_pre(const Params& p, LAS unsigned char* lds, int item, int next_item, int tid, int wave, int lane, h16 (&raw)[48]) {
;     ...
;         for (int i = 0; i < 8; ++i) wv[i] = (float)raw[i * 6 + 2];
;         lp[0] = wv[0];
; #pragma unroll
;         for (int i = 1; i < 8; ++i) lp[i] = lp[i - 1] * wv[i];
;         GT[g * 64 + k] = lp[7];
;         BAR_LDS();
;         float bs = 1.f, WL = 1.f;
; #pragma unroll
;         for (int q = 0; q < 8; ++q) { const float gq = GT[q * 64 + k]; if (q < g) bs *= gq; WL *= gq; }
;     ...
;         { float WL = 1.f;
; #pragma unroll
;           for (int q = 0; q < 8; ++q) WL *= GT[q * 64 + ar];
; #pragma unroll
;           for (int nt = 0; nt < 2; ++nt) { const int b0 = 32 * (wave & 1) + 16 * nt + 4 * fq; f32x4 v = acc[nt];
; #pragma unroll
;               for (int jj = 0; jj < 4; ++jj) if (b0 + jj == ar) v[jj] += WL;
;               u32x2 w; w.x = pk2(v.x, v.y); w.y = pk2(v.z, v.w); *(u32x2*)(base + (size_t)(ar * 6 + 0) * 64 + b0) = w; } }
;         acc[0] = (f32x4){0.f, 0.f, 0.f, 0.f}; acc[1] = acc[0];
;         mm64(BhT, P1T, acc, wave, fr, fq); mm64(KhT, VT, acc, wave, fr, fq);
; #pragma unroll
;         for (int nt = 0; nt < 2; ++nt) { const int b0 = 32 * (wave & 1) + 16 * nt + 4 * fq; const f32x4 v = acc[nt];
;             u32x2 w; w.x = pk2(v.x, v.y); w.y = pk2(v.z, v.w); *(u32x2*)(base + (size_t)(ar * 6 + 1) * 64 + b0) = w; }
;     }
;     BAR_LDS();
	v_mfma_f32_16x16x32_bf16 v[4:7], v[4:7], v[36:39], v[8:11]
	v_mfma_f32_16x16x32_bf16 v[8:11], v[220:223], v[36:39], v[16:19]
	s_nop 0
	s_waitcnt lgkmcnt(6)
	v_mul_f32_e32 v14, v224, v225
	s_nop 0
	s_waitcnt lgkmcnt(5)
	v_mul_f32_e32 v12, v14, v226
	v_mul_f32_e32 v14, v12, v227
	s_nop 0
	s_waitcnt lgkmcnt(4)
	v_mul_f32_e32 v12, v14, v228
	v_mul_f32_e32 v14, v12, v229
	s_nop 0
	s_waitcnt lgkmcnt(3)
	v_mul_f32_e32 v12, v14, v230
	v_fma_f32 v16, v12, v231, v4
	v_cndmask_b32_e64 v4, v4, v16, s[12:13]
	v_readlane_b32 s12, v244, 53
	v_fma_f32 v16, v12, v231, v5
	v_readlane_b32 s13, v244, 54
	v_lshl_add_u64 v[14:15], s[80:81], 0, v[30:31]
	s_nop 0
	v_cndmask_b32_e64 v5, v5, v16, s[12:13]
	v_readlane_b32 s12, v244, 55
	v_fma_f32 v16, v12, v231, v6
	v_readlane_b32 s13, v244, 56
	v_cvt_pk_bf16_f32 v4, v4, v5
	s_nop 0
	v_cndmask_b32_e64 v6, v6, v16, s[12:13]
	v_fma_f32 v16, v12, v231, v7
	v_cndmask_b32_e64 v7, v7, v16, s[56:57]
	v_cvt_pk_bf16_f32 v5, v6, v7
	v_lshl_add_u64 v[6:7], v[14:15], 0, v[34:35]
	global_store_dwordx2 v[6:7], v[4:5], off
	v_fma_f32 v4, v12, v231, v8
	v_fma_f32 v5, v12, v231, v9
	v_cndmask_b32_e64 v4, v8, v4, s[88:89]
	v_cndmask_b32_e64 v5, v9, v5, s[4:5]
	v_fma_f32 v8, v12, v231, v10
	v_fma_f32 v9, v12, v231, v11
	v_cndmask_b32_e64 v8, v10, v8, s[0:1]
	v_cndmask_b32_e64 v9, v11, v9, s[68:69]
	v_cvt_pk_bf16_f32 v4, v4, v5
	v_cvt_pk_bf16_f32 v5, v8, v9
	global_store_dwordx2 v[6:7], v[4:5], off offset:32
	s_nop 0
	s_nop 0
	s_nop 0
	s_waitcnt lgkmcnt(1)
	v_mfma_f32_16x16x32_bf16 v[8:11], v[236:239], v[232:235], 0
	s_waitcnt lgkmcnt(0)
	v_mfma_f32_16x16x32_bf16 v[4:7], v[240:243], v[232:235], 0
	ds_read_b128 v[12:15], v91 offset:18496
	ds_read_b128 v[16:19], v161 offset:36928
	ds_read_b128 v[220:223], v161 offset:39232
	ds_read_b128 v[224:227], v91 offset:55296
	ds_read_b128 v[228:231], v161 offset:46080
	ds_read_b128 v[232:235], v161 offset:48384
	s_waitcnt lgkmcnt(4)
	v_mfma_f32_16x16x32_bf16 v[8:11], v[16:19], v[12:15], v[8:11]
	s_nop 0
	s_waitcnt lgkmcnt(3)
	v_mfma_f32_16x16x32_bf16 v[4:7], v[220:223], v[12:15], v[4:7]
	s_nop 0
	s_nop 0
	s_waitcnt lgkmcnt(1)
	v_mfma_f32_16x16x32_bf16 v[8:11], v[228:231], v[224:227], v[8:11]
	s_nop 0
	s_waitcnt lgkmcnt(0)
	v_mfma_f32_16x16x32_bf16 v[4:7], v[232:235], v[224:227], v[4:7]
	ds_read_b128 v[12:15], v91 offset:55360
	ds_read_b128 v[16:19], v161 offset:46144
	s_waitcnt lgkmcnt(0)
	v_mfma_f32_16x16x32_bf16 v[8:11], v[16:19], v[12:15], v[8:11]
	ds_read_b128 v[16:19], v161 offset:48448
	s_waitcnt lgkmcnt(0)
	v_mfma_f32_16x16x32_bf16 v[4:7], v[16:19], v[12:15], v[4:7]
	v_lshl_add_u64 v[12:13], s[80:81], 0, v[32:33]
	s_nop 3
	v_cvt_pk_bf16_f32 v8, v8, v9
	v_cvt_pk_bf16_f32 v9, v10, v11
	v_lshl_add_u64 v[10:11], v[12:13], 0, v[34:35]
	v_cvt_pk_bf16_f32 v4, v4, v5
	v_cvt_pk_bf16_f32 v5, v6, v7
	global_store_dwordx2 v[10:11], v[8:9], off
	global_store_dwordx2 v[10:11], v[4:5], off offset:32
	s_waitcnt lgkmcnt(0)
	s_barrier
	s_cbranch_vccnz .LBB0_945
.LBB0_923:
	s_waitcnt vmcnt(45)
	v_cvt_f32_f16_e32 v10, v42
	s_waitcnt vmcnt(39)
	v_cvt_f32_f16_e32 v4, v48
	s_waitcnt vmcnt(33)
	v_cvt_f32_f16_e32 v5, v54
	s_waitcnt vmcnt(27)
	v_cvt_f32_f16_e32 v6, v60
	s_waitcnt vmcnt(21)
	v_cvt_f32_f16_e32 v12, v68
	s_waitcnt vmcnt(15)
	v_cvt_f32_f16_e32 v13, v75
	v_mul_f32_e32 v11, v10, v4
	s_waitcnt vmcnt(9)
	v_cvt_f32_f16_e32 v14, v83
	v_mul_f32_e32 v34, v11, v5
	s_waitcnt vmcnt(3)
	v_cvt_f32_f16_e32 v15, v89
	v_mul_f32_e32 v35, v34, v6
	v_mul_f32_e32 v12, v35, v12
	v_mul_f32_e32 v13, v12, v13
	v_mul_f32_e32 v4, v13, v14
	v_mul_f32_e32 v5, v4, v15
	ds_write_b32 v63, v5
	s_waitcnt lgkmcnt(0)
	s_barrier
	ds_read2st64_b32 v[14:15], v65 offset1:1
	ds_read2st64_b32 v[220:221], v65 offset0:2 offset1:3
	ds_read2st64_b32 v[222:223], v65 offset0:4 offset1:5
	ds_read2st64_b32 v[224:225], v65 offset0:6 offset1:7
	v_readlane_b32 s14, v244, 33
	v_readlane_b32 s15, v244, 34
	v_cvt_f32_f16_e64 v37, -v40
	v_cvt_f32_f16_e32 v36, v41
	s_waitcnt lgkmcnt(3)
	v_cndmask_b32_e64 v6, 1.0, v14, s[82:83]
	v_mul_f32_e32 v16, v6, v15
	v_cndmask_b32_e64 v6, v6, v16, s[14:15]
	v_mul_f32_e32 v16, v14, v15
	s_nop 0
	v_readlane_b32 s14, v244, 35
	v_readlane_b32 s15, v244, 36
	v_cvt_f32_f16_e32 v17, v51
	v_cvt_f32_f16_e64 v170, -v46
	s_waitcnt lgkmcnt(2)
	v_mul_f32_e32 v168, v220, v6
	v_cndmask_b32_e64 v6, v6, v168, s[14:15]
	v_readlane_b32 s14, v244, 37
	v_mul_f32_e32 v14, v16, v220
	v_mul_f32_e32 v16, v221, v6
	v_readlane_b32 s15, v244, 38
	v_cvt_f32_f16_e32 v171, v47
	v_cvt_f32_f16_e32 v174, v53
	v_cndmask_b32_e64 v6, v6, v16, s[14:15]
	v_mul_f32_e32 v16, v14, v221
	s_nop 0
	v_readlane_b32 s14, v244, 39
	v_readlane_b32 s15, v244, 40
	v_cvt_f32_f16_e32 v18, v55
	v_cvt_f32_f16_e32 v19, v61
	s_waitcnt lgkmcnt(1)
	v_mul_f32_e32 v168, v222, v6
	v_cndmask_b32_e64 v6, v6, v168, s[14:15]
	v_readlane_b32 s14, v244, 41
	v_mul_f32_e32 v14, v16, v222
	v_mul_f32_e32 v16, v223, v6
	v_readlane_b32 s15, v244, 42
	v_cvt_f32_f16_e32 v176, v59
	v_cvt_f32_f16_e32 v177, v67
	v_cndmask_b32_e64 v6, v6, v16, s[14:15]
	v_mul_f32_e32 v16, v14, v223
	s_nop 0
	v_readlane_b32 s14, v244, 43
	v_readlane_b32 s15, v244, 44
	v_cvt_f32_f16_e32 v169, v73
	v_cvt_f32_f16_e32 v8, v69
	s_waitcnt lgkmcnt(0)
; __device__ __forceinline__ unsigned pk2(float lo, float hi) { const f32x2c v = {lo, hi}; const bf16x2c b = __builtin_convertvector(v, bf16x2c); return __builtin_bit_cast(unsigned, b); }
; __device__ __forceinline__ void chunk_pre(const Params& p, LAS unsigned char* lds, int item, int next_item, int tid, int wave, int lane, h16 (&raw)[48]) {
;     ...
;         float bhv[8], khv[8], vtv[8], atv[8];
; #pragma unroll
;         for (int i = 0; i < 8; ++i) {
;             const int t = 8 * g + i;
;             const float kk = (float)raw[i * 6 + 0], wr = (float)raw[i * 6 + 1], bb = (float)raw[i * 6 + 3], kx = (float)raw[i * 6 + 4], vv = (float)raw[i * 6 + 5];
;             const float Wt = bs * lp[i], Wp = (i == 0) ? bs : bs * lp[i - 1], iW = 1.f / Wt;
;             atv[i] = -kk * Wp; At[t * MS + k] = (bf16_t)(pk2(-kk * Wp, 0.f) & 0xffffu); Rt[t * MS + k] = (bf16_t)(pk2(wr * Wp, 0.f) & 0xffffu);
;             Bt[t * MS + k] = (bf16_t)(pk2(bb * iW, 0.f) & 0xffffu); Kt[t * MS + k] = (bf16_t)(pk2(kx * iW, 0.f) & 0xffffu);
;             bhv[i] = bb * iW * WL; khv[i] = kx * iW * WL; vtv[i] = vv;
	v_mul_f32_e32 v168, v224, v6
	v_cndmask_b32_e64 v6, v6, v168, s[14:15]
	v_readlane_b32 s14, v244, 45
	v_mul_f32_e32 v14, v16, v224
	v_mul_f32_e32 v16, v225, v6
	v_readlane_b32 s15, v244, 46
	v_cvt_f32_f16_e32 v9, v76
	v_cvt_f32_f16_e32 v7, v45
	v_cndmask_b32_e64 v16, v6, v16, s[14:15]
	v_mul_f32_e32 v168, v16, v37
	v_mul_f32_e32 v6, v14, v225
	v_cvt_pk_bf16_f32 v14, v168, s0
	ds_write_b16 v74, v14
	v_mul_f32_e32 v14, v16, v36
	v_pk_mul_f32 v[36:37], v[16:17], v[10:11] op_sel_hi:[0,1]
	v_div_scale_f32 v10, s[14:15], v37, v37, 1.0
	v_rcp_f32_e32 v11, v10
	v_cvt_pk_bf16_f32 v14, v14, s0
	ds_write_b16 v74, v14 offset:27648
	v_cvt_f32_f16_e32 v14, v43
	v_fma_f32 v172, -v10, v11, 1.0
	v_fmac_f32_e32 v11, v172, v11
	v_div_scale_f32 v172, vcc, 1.0, v37, 1.0
	v_mul_f32_e32 v173, v172, v11
	v_fma_f32 v175, -v10, v173, v172
	v_fmac_f32_e32 v173, v175, v11
	v_fma_f32 v10, -v10, v173, v172
	v_div_fmas_f32 v10, v10, v11, v173
	v_div_fixup_f32 v173, v10, v37, 1.0
	v_div_scale_f32 v10, s[14:15], v36, v36, 1.0
	v_rcp_f32_e32 v11, v10
	v_cvt_f32_f16_e32 v15, v49
	v_mul_f32_e32 v170, v36, v170
	v_pk_mul_f32 v[12:13], v[12:13], v[16:17] op_sel_hi:[1,0]
	v_fma_f32 v172, -v10, v11, 1.0
	v_fmac_f32_e32 v11, v172, v11
	v_div_scale_f32 v172, vcc, 1.0, v36, 1.0
	v_mul_f32_e32 v175, v172, v11
	v_fma_f32 v178, -v10, v175, v172
	v_fmac_f32_e32 v175, v178, v11
	v_fma_f32 v10, -v10, v175, v172
	v_div_fmas_f32 v10, v10, v11, v175
	v_div_fixup_f32 v172, v10, v36, 1.0
	v_pk_mul_f32 v[10:11], v[172:173], v[14:15]
	v_cvt_f32_f16_e32 v15, v50
	v_cvt_pk_bf16_f32 v14, v10, s0
	ds_write_b16 v74, v14 offset:9216
	v_cvt_pk_bf16_f32 v14, v170, s0
	ds_write_b16 v74, v14 offset:144
	v_mul_f32_e32 v14, v36, v171
	v_cvt_pk_bf16_f32 v14, v14, s0
	ds_write_b16 v74, v14 offset:27792
	v_cvt_pk_bf16_f32 v14, v11, s0
	ds_write_b16 v74, v14 offset:9360
	v_cvt_f32_f16_e32 v14, v44
	v_mul_f32_e32 v169, v12, v169
	v_cvt_pk_bf16_f32 v169, v169, s0
	ds_write_b16 v74, v169 offset:28368
	v_pk_mul_f32 v[14:15], v[172:173], v[14:15]
	v_pk_mul_f32 v[172:173], v[34:35], v[16:17] op_sel_hi:[1,0]
	v_cvt_pk_bf16_f32 v171, v14, s0
	v_div_scale_f32 v34, s[14:15], v173, v173, 1.0
	v_rcp_f32_e32 v35, v34
	ds_write_b16 v74, v171 offset:18432
	v_cvt_pk_bf16_f32 v171, v15, s0
	ds_write_b16 v74, v171 offset:18576
	v_mul_f32_e32 v171, v37, v174
	v_cvt_pk_bf16_f32 v171, v171, s0
	ds_write_b16 v74, v171 offset:27936
	v_fma_f32 v171, -v34, v35, 1.0
	v_fmac_f32_e32 v35, v171, v35
	v_div_scale_f32 v171, vcc, 1.0, v173, 1.0
	v_mul_f32_e32 v174, v171, v35
	v_fma_f32 v175, -v34, v174, v171
	v_fmac_f32_e32 v174, v175, v35
	v_fma_f32 v34, -v34, v174, v171
	v_div_fmas_f32 v34, v34, v35, v174
	v_div_fixup_f32 v175, v34, v173, 1.0
	v_div_scale_f32 v34, s[14:15], v172, v172, 1.0
	v_rcp_f32_e32 v35, v34
	v_pk_mov_b32 v[36:37], v[36:37], v[172:173] op_sel:[1,0]
	v_cvt_f32_f16_e32 v167, v82
	v_pk_mul_f32 v[4:5], v[4:5], v[16:17] op_sel_hi:[1,0]
	v_fma_f32 v171, -v34, v35, 1.0
	v_fmac_f32_e32 v35, v171, v35
	v_div_scale_f32 v171, vcc, 1.0, v172, 1.0
	v_mul_f32_e32 v174, v171, v35
	v_fma_f32 v178, -v34, v174, v171
	v_fmac_f32_e32 v174, v178, v35
	v_fma_f32 v34, -v34, v174, v171
	v_div_fmas_f32 v34, v34, v35, v174
	v_div_fixup_f32 v174, v34, v172, 1.0
	v_pk_mul_f32 v[34:35], v[174:175], v[18:19]
	v_cvt_f32_f16_e64 v19, -v58
	v_cvt_pk_bf16_f32 v18, v34, s0
	ds_write_b16 v74, v18 offset:9504
	v_cvt_f32_f16_e64 v18, -v52
	v_div_scale_f32 v16, s[14:15], v5, v5, 1.0
	v_cvt_f32_f16_e32 v166, v88
	v_pk_mul_f32 v[18:19], v[36:37], v[18:19]
	v_cvt_f32_f16_e32 v37, v62
	v_cvt_pk_bf16_f32 v36, v18, s0
	ds_write_b16 v74, v36 offset:288
	v_cvt_pk_bf16_f32 v36, v19, s0
	ds_write_b16 v74, v36 offset:432
	v_mul_f32_e32 v36, v172, v176
	v_cvt_pk_bf16_f32 v36, v36, s0
	ds_write_b16 v74, v36 offset:28080
	v_cvt_pk_bf16_f32 v36, v35, s0
	ds_write_b16 v74, v36 offset:9648
	v_cvt_f32_f16_e32 v36, v56
	v_cvt_f32_f16_e64 v180, -v81
	v_cvt_f32_f16_e64 v181, -v87
	v_cvt_f32_f16_e32 v20, v57
	v_pk_mul_f32 v[36:37], v[174:175], v[36:37]
	v_cvt_f32_f16_e32 v38, v64
	v_cvt_pk_bf16_f32 v171, v36, s0
	ds_write_b16 v74, v171 offset:18720
	v_cvt_pk_bf16_f32 v171, v37, s0
	ds_write_b16 v74, v171 offset:18864
	v_mul_f32_e32 v171, v173, v177
	v_cvt_pk_bf16_f32 v171, v171, s0
	ds_write_b16 v74, v171 offset:28224
	v_div_scale_f32 v171, s[14:15], v13, v13, 1.0
	v_rcp_f32_e32 v174, v171
	v_pk_mov_b32 v[172:173], v[172:173], v[12:13] op_sel:[1,0]
	v_cvt_f32_f16_e32 v39, v71
	v_cvt_f32_f16_e32 v163, v80
	v_fma_f32 v175, -v171, v174, 1.0
	v_fmac_f32_e32 v174, v175, v174
	v_div_scale_f32 v175, vcc, 1.0, v13, 1.0
	v_mul_f32_e32 v176, v175, v174
	v_fma_f32 v177, -v171, v176, v175
	v_fmac_f32_e32 v176, v177, v174
	v_fma_f32 v171, -v171, v176, v175
	v_div_fmas_f32 v171, v171, v174, v176
	v_div_fixup_f32 v175, v171, v13, 1.0
	v_div_scale_f32 v171, s[14:15], v12, v12, 1.0
	v_rcp_f32_e32 v174, v171
	v_cvt_f32_f16_e32 v164, v86
	s_waitcnt vmcnt(0)
; #define LAS __attribute__((address_space(3)))
; __device__ __forceinline__ unsigned pk2(float lo, float hi) { const f32x2c v = {lo, hi}; const bf16x2c b = __builtin_convertvector(v, bf16x2c); return __builtin_bit_cast(unsigned, b); }
; __device__ __forceinline__ void chunk_pre(const Params& p, LAS unsigned char* lds, int item, int next_item, int tid, int wave, int lane, h16 (&raw)[48]) {
;     ...
;         for (int i = 0; i < 8; ++i) {
;             const int t = 8 * g + i;
;             const float kk = (float)raw[i * 6 + 0], wr = (float)raw[i * 6 + 1], bb = (float)raw[i * 6 + 3], kx = (float)raw[i * 6 + 4], vv = (float)raw[i * 6 + 5];
;             const float Wt = bs * lp[i], Wp = (i == 0) ? bs : bs * lp[i - 1], iW = 1.f / Wt;
;             atv[i] = -kk * Wp; At[t * MS + k] = (bf16_t)(pk2(-kk * Wp, 0.f) & 0xffffu); Rt[t * MS + k] = (bf16_t)(pk2(wr * Wp, 0.f) & 0xffffu);
;             Bt[t * MS + k] = (bf16_t)(pk2(bb * iW, 0.f) & 0xffffu); Kt[t * MS + k] = (bf16_t)(pk2(kx * iW, 0.f) & 0xffffu);
;             bhv[i] = bb * iW * WL; khv[i] = kx * iW * WL; vtv[i] = vv;
;         }
;         *(LAS u32x4*)(BhT + k * MS + 8 * g) = (u32x4){pk2(bhv[0], bhv[1]), pk2(bhv[2], bhv[3]), pk2(bhv[4], bhv[5]), pk2(bhv[6], bhv[7])};
;         *(LAS u32x4*)(KhT + k * MS + 8 * g) = (u32x4){pk2(khv[0], khv[1]), pk2(khv[2], khv[3]), pk2(khv[4], khv[5]), pk2(khv[6], khv[7])};
;         *(LAS u32x4*)(VT + k * MS + 8 * g) = (u32x4){pk2(vtv[0], vtv[1]), pk2(vtv[2], vtv[3]), pk2(vtv[4], vtv[5]), pk2(vtv[6], vtv[7])};
;         *(LAS u32x4*)(AtT + k * MS + 8 * g) = (u32x4){pk2(atv[0], atv[1]), pk2(atv[2], atv[3]), pk2(atv[4], atv[5]), pk2(atv[6], atv[7])};
;     }
;     if (next_item >= 0) chunk_load(p, next_item, tid, raw);
	v_cvt_f32_f16_e32 v165, v93
	s_add_i32 s50, s45, s94
	v_fma_f32 v176, -v171, v174, 1.0
	v_fmac_f32_e32 v174, v176, v174
	v_div_scale_f32 v176, vcc, 1.0, v12, 1.0
	v_mul_f32_e32 v177, v176, v174
	v_fma_f32 v178, -v171, v177, v176
	v_fmac_f32_e32 v177, v178, v174
	v_fma_f32 v171, -v171, v177, v176
	v_div_fmas_f32 v171, v171, v174, v177
	v_cvt_f32_f16_e64 v176, -v66
	v_cvt_f32_f16_e64 v177, -v72
	v_div_fixup_f32 v174, v171, v12, 1.0
	v_pk_mul_f32 v[8:9], v[174:175], v[8:9]
	s_cmpk_gt_i32 s50, 0xfff
	v_cvt_pk_bf16_f32 v171, v8, s0
	v_pk_mul_f32 v[172:173], v[172:173], v[176:177]
	v_cvt_pk_bf16_f32 v169, v9, s0
	v_pk_mul_f32 v[176:177], v[6:7], v[8:9] op_sel_hi:[0,1]
	v_cvt_f32_f16_e32 v8, v70
	v_cvt_f32_f16_e32 v9, v78
	ds_write_b16 v74, v169 offset:9936
	ds_write_b16 v74, v171 offset:9792
	v_cvt_pk_bf16_f32 v171, v172, s0
	v_pk_mul_f32 v[8:9], v[174:175], v[8:9]
	ds_write_b16 v74, v171 offset:576
	v_cvt_pk_bf16_f32 v169, v8, s0
	v_pk_mul_f32 v[174:175], v[6:7], v[8:9] op_sel_hi:[0,1]
	v_mul_f32_e32 v8, v13, v167
	v_rcp_f32_e32 v167, v16
	ds_write_b16 v74, v169 offset:19008
	v_cvt_pk_bf16_f32 v169, v9, s0
	ds_write_b16 v74, v169 offset:19152
	v_fma_f32 v169, -v16, v167, 1.0
	v_cvt_pk_bf16_f32 v171, v173, s0
	v_fmac_f32_e32 v167, v169, v167
	v_div_scale_f32 v169, vcc, 1.0, v5, 1.0
	ds_write_b16 v74, v171 offset:720
	v_mul_f32_e32 v171, v169, v167
	v_fma_f32 v178, -v16, v171, v169
	v_fmac_f32_e32 v171, v178, v167
	v_fma_f32 v16, -v16, v171, v169
	v_div_fmas_f32 v16, v16, v167, v171
	v_div_fixup_f32 v179, v16, v5, 1.0
	v_div_scale_f32 v16, s[14:15], v4, v4, 1.0
	v_rcp_f32_e32 v167, v16
	v_cvt_pk_bf16_f32 v8, v8, s0
	ds_write_b16 v74, v8 offset:28512
	v_cvt_f32_f16_e32 v8, v84
	v_fma_f32 v169, -v16, v167, 1.0
	v_fmac_f32_e32 v167, v169, v167
	v_div_scale_f32 v169, vcc, 1.0, v4, 1.0
	v_mul_f32_e32 v171, v169, v167
	v_fma_f32 v178, -v16, v171, v169
	v_cvt_f32_f16_e32 v9, v90
	v_fmac_f32_e32 v171, v178, v167
	v_fma_f32 v16, -v16, v171, v169
	v_div_fmas_f32 v16, v16, v167, v171
	v_pk_mov_b32 v[12:13], v[12:13], v[4:5] op_sel:[1,0]
	v_div_fixup_f32 v178, v16, v4, 1.0
	v_pk_mul_f32 v[12:13], v[12:13], v[180:181]
	v_mul_f32_e32 v4, v4, v166
	v_pk_mul_f32 v[8:9], v[178:179], v[8:9]
	v_cvt_pk_bf16_f32 v5, v12, s0
	v_cvt_pk_bf16_f32 v4, v4, s0
	ds_write_b16 v74, v5 offset:864
	v_cvt_pk_bf16_f32 v5, v13, s0
	ds_write_b16 v74, v4 offset:28656
	v_cvt_pk_bf16_f32 v4, v9, s0
	v_cvt_pk_bf16_f32 v16, v8, s0
	ds_write_b16 v74, v5 offset:1008
	ds_write_b16 v74, v4 offset:10224
	v_pk_mul_f32 v[4:5], v[6:7], v[8:9] op_sel_hi:[0,1]
	v_cvt_f32_f16_e32 v8, v85
	v_cvt_f32_f16_e32 v9, v92
	s_cselect_b64 s[10:11], -1, 0
	s_cmpk_lt_i32 s50, 0x1000
	v_pk_mul_f32 v[10:11], v[6:7], v[10:11] op_sel_hi:[0,1]
	v_pk_mul_f32 v[8:9], v[178:179], v[8:9]
	v_pk_mul_f32 v[34:35], v[6:7], v[34:35] op_sel_hi:[0,1]
	ds_write_b16 v74, v16 offset:10080
	v_cvt_pk_bf16_f32 v16, v8, s0
	s_cselect_b32 s12, s50, -1
	v_pk_mul_f32 v[14:15], v[6:7], v[14:15] op_sel_hi:[0,1]
	v_pk_mul_f32 v[36:37], v[6:7], v[36:37] op_sel_hi:[0,1]
	ds_write_b16 v74, v16 offset:19296
	v_cvt_pk_bf16_f32 v16, v9, s0
	v_pk_mul_f32 v[166:167], v[6:7], v[8:9] op_sel_hi:[0,1]
	v_cvt_pk_bf16_f32 v8, v10, v11
	v_cvt_pk_bf16_f32 v9, v34, v35
	v_cvt_pk_bf16_f32 v10, v176, v177
	v_cvt_pk_bf16_f32 v11, v4, v5
	v_cvt_pk_bf16_f32 v4, v7, v17
	v_cvt_pk_bf16_f32 v5, v20, v38
	v_cvt_pk_bf16_f32 v6, v39, v163
	v_cvt_pk_bf16_f32 v7, v164, v165
	ds_write_b16 v74, v16 offset:19440
	ds_write_b128 v77, v[8:11] offset:36864
	v_cvt_pk_bf16_f32 v8, v14, v15
	v_cvt_pk_bf16_f32 v9, v36, v37
	v_cvt_pk_bf16_f32 v10, v174, v175
	v_cvt_pk_bf16_f32 v11, v166, v167
	ds_write_b128 v77, v[4:7] offset:55296
	v_cvt_pk_bf16_f32 v4, v168, v170
	v_cvt_pk_bf16_f32 v5, v18, v19
	v_cvt_pk_bf16_f32 v6, v172, v173
	v_cvt_pk_bf16_f32 v7, v12, v13
	s_cmp_lt_i32 s12, 0
	ds_write_b128 v77, v[8:11] offset:46080
	ds_write_b128 v79, v[4:7]
	s_cbranch_scc1 .LBB0_925
	s_lshr_b32 s8, s12, 7
	s_lshl_b64 s[14:15], s[8:9], 13
	s_lshl_b32 s8, s12, 6
	s_and_b32 s8, s8, 0x1fc0
	s_or_b32 s8, s14, s8
	v_mad_u64_u32 v[4:5], s[12:13], s8, v160, v[22:23]
	s_mul_i32 s8, s15, 0x300
	v_add_u32_e32 v5, s8, v5
	global_load_ushort v40, v[4:5], off
	global_load_ushort v41, v[4:5], off offset:128
	global_load_ushort v42, v[4:5], off offset:256
	global_load_ushort v43, v[4:5], off offset:384
	global_load_ushort v44, v[4:5], off offset:512
	global_load_ushort v45, v[4:5], off offset:640
	global_load_ushort v46, v[4:5], off offset:768
	global_load_ushort v47, v[4:5], off offset:896
	global_load_ushort v48, v[4:5], off offset:1024
	global_load_ushort v49, v[4:5], off offset:1152
	global_load_ushort v50, v[4:5], off offset:1280
	global_load_ushort v51, v[4:5], off offset:1408
	global_load_ushort v52, v[4:5], off offset:1536
	global_load_ushort v53, v[4:5], off offset:1664
	global_load_ushort v54, v[4:5], off offset:1792
	global_load_ushort v55, v[4:5], off offset:1920
	global_load_ushort v56, v[4:5], off offset:2048
	global_load_ushort v57, v[4:5], off offset:2176
	global_load_ushort v58, v[4:5], off offset:2304
	global_load_ushort v59, v[4:5], off offset:2432
	global_load_ushort v60, v[4:5], off offset:2560
	global_load_ushort v61, v[4:5], off offset:2688
	global_load_ushort v62, v[4:5], off offset:2816
	global_load_ushort v64, v[4:5], off offset:2944
	global_load_ushort v66, v[4:5], off offset:3072
	global_load_ushort v67, v[4:5], off offset:3200
	global_load_ushort v68, v[4:5], off offset:3328
	global_load_ushort v69, v[4:5], off offset:3456
	global_load_ushort v70, v[4:5], off offset:3584
	global_load_ushort v71, v[4:5], off offset:3712
	global_load_ushort v72, v[4:5], off offset:3840
	global_load_ushort v73, v[4:5], off offset:3968
	v_add_co_u32_e32 v4, vcc, s53, v4
	s_nop 1
	v_addc_co_u32_e32 v5, vcc, 0, v5, vcc
	global_load_ushort v75, v[4:5], off
	global_load_ushort v76, v[4:5], off offset:128
	global_load_ushort v78, v[4:5], off offset:256
	global_load_ushort v80, v[4:5], off offset:384
	global_load_ushort v81, v[4:5], off offset:512
	global_load_ushort v82, v[4:5], off offset:640
	global_load_ushort v83, v[4:5], off offset:768
	global_load_ushort v84, v[4:5], off offset:896
	global_load_ushort v85, v[4:5], off offset:1024
	global_load_ushort v86, v[4:5], off offset:1152
	global_load_ushort v87, v[4:5], off offset:1280
	global_load_ushort v88, v[4:5], off offset:1408
	global_load_ushort v89, v[4:5], off offset:1536
	global_load_ushort v90, v[4:5], off offset:1664
	global_load_ushort v92, v[4:5], off offset:1792
	global_load_ushort v93, v[4:5], off offset:1920
; #define LAS __attribute__((address_space(3)))
; #define BAR_LDS() do { asm volatile("s_waitcnt lgkmcnt(0)" ::: "memory"); __builtin_amdgcn_s_barrier(); asm volatile("" ::: "memory"); } while (0)
; __device__ __forceinline__ void st_bf4(LAS bf16_t* p, f32x4 v) { u32x2 w; w.x = pk2(v.x, v.y); w.y = pk2(v.z, v.w); *(LAS u32x2*)p = w; }
; __device__ __forceinline__ void chunk_pre(const Params& p, LAS unsigned char* lds, int item, int next_item, int tid, int wave, int lane, h16 (&raw)[48]) {
;     ...
;     const int a0 = 16 * (wave >> 1), ar = a0 + fr;
;     {
;         f32x4 acc[2];
; #pragma unroll
;         for (int which = 0; which < 4; ++which) {
;             acc[0] = (f32x4){0.f, 0.f, 0.f, 0.f}; acc[1] = acc[0];
;             mm64((which & 1) ? Kt : Bt, (which & 2) ? Rt : At, acc, wave, fr, fq);
; #pragma unroll
;             for (int nt = 0; nt < 2; ++nt) { const int s0 = 32 * (wave & 1) + 16 * nt + 4 * fq; f32x4 v = acc[nt];
; #pragma unroll
;                 for (int jj = 0; jj < 4; ++jj) { const bool keep = (which & 2) ? (s0 + jj <= ar) : (s0 + jj < ar); if (!keep) v[jj] = 0.f; }
;                 if (which == 0) *(LAS f32x4*)(Mab + ar * 64 + s0) = v;
;                 else st_bf4(((which == 1) ? Mak : (which == 2) ? Mrb : Mrk) + ar * MS + s0, v); }
;         }
;     }
;     BAR_LDS();
;     {
;         f32x4 acc[2]; acc[0] = (f32x4){0.f, 0.f, 0.f, 0.f}; acc[1] = acc[0];
;         mm64(Mak, VT, acc, wave, fr, fq);
; #pragma unroll
;         for (int nt = 0; nt < 2; ++nt) st_bf4(RH2T + ar * MS + 32 * (wave & 1) + 16 * nt + 4 * fq, acc[nt]);
;     }
;     for (int e = tid; e < 6 * 256; e += 512) { const int ub = e >> 8, i = (e >> 4) & 15, j = e & 15;
;         const int r = ub < 3 ? 0 : ub < 5 ? 1 : 2, c = ub < 3 ? ub + 1 : ub < 5 ? ub - 1 : 3; Tb[(16 * r + i) * MS + 16 * c + j] = 0; }
;     if (tid < 64) {
.LBB0_925:
	s_waitcnt lgkmcnt(0)
	s_barrier
	ds_read_b128 v[4:7], v91
	ds_read_b128 v[8:11], v161 offset:9216
	ds_read_b128 v[12:15], v161 offset:11520
	ds_read_b128 v[220:223], v91 offset:64
	ds_read_b128 v[16:19], v161 offset:9280
	ds_read_b128 v[224:227], v161 offset:11584
	s_or_b64 vcc, s[72:73], s[20:21]
	s_waitcnt lgkmcnt(4)
	v_mfma_f32_16x16x32_bf16 v[8:11], v[8:11], v[4:7], 0
	s_or_b64 s[80:81], s[76:77], s[24:25]
	s_waitcnt lgkmcnt(3)
	v_mfma_f32_16x16x32_bf16 v[4:7], v[12:15], v[4:7], 0
	s_nop 0
	s_nop 0
	s_waitcnt lgkmcnt(1)
	v_mfma_f32_16x16x32_bf16 v[8:11], v[16:19], v[220:223], v[8:11]
	s_nop 0
	s_waitcnt lgkmcnt(0)
	v_mfma_f32_16x16x32_bf16 v[4:7], v[224:227], v[220:223], v[4:7]
	s_nop 4
	v_cndmask_b32_e64 v11, 0, v11, s[22:23]
	v_cndmask_b32_e64 v10, 0, v10, s[70:71]
	v_cndmask_b32_e64 v9, 0, v9, s[72:73]
	v_cndmask_b32_e32 v8, 0, v8, vcc
	v_cndmask_b32_e64 v7, 0, v7, s[26:27]
	v_cndmask_b32_e64 v6, 0, v6, s[74:75]
	v_cndmask_b32_e64 v5, 0, v5, s[76:77]
	v_cndmask_b32_e64 v4, 0, v4, s[80:81]
	ds_write_b128 v94, v[8:11]
	ds_write_b128 v94, v[4:7] offset:64
	ds_read_b128 v[4:7], v91
	ds_read_b128 v[8:11], v161 offset:18432
	ds_read_b128 v[12:15], v161 offset:20736
	ds_read_b128 v[220:223], v91 offset:64
	ds_read_b128 v[16:19], v161 offset:18496
	ds_read_b128 v[224:227], v161 offset:20800
	s_waitcnt lgkmcnt(4)
	v_mfma_f32_16x16x32_bf16 v[8:11], v[8:11], v[4:7], 0
	s_waitcnt lgkmcnt(3)
	v_mfma_f32_16x16x32_bf16 v[4:7], v[12:15], v[4:7], 0
	s_nop 0
	s_nop 0
	s_waitcnt lgkmcnt(1)
	v_mfma_f32_16x16x32_bf16 v[8:11], v[16:19], v[220:223], v[8:11]
	s_nop 0
	s_waitcnt lgkmcnt(0)
	v_mfma_f32_16x16x32_bf16 v[4:7], v[224:227], v[220:223], v[4:7]
	s_nop 4
	v_cndmask_b32_e64 v11, 0, v11, s[22:23]
	v_cndmask_b32_e64 v10, 0, v10, s[70:71]
	v_cndmask_b32_e64 v9, 0, v9, s[72:73]
	v_cndmask_b32_e32 v8, 0, v8, vcc
	v_cndmask_b32_e64 v7, 0, v7, s[26:27]
	v_cndmask_b32_e64 v6, 0, v6, s[74:75]
	v_cndmask_b32_e64 v5, 0, v5, s[76:77]
	v_cndmask_b32_e64 v4, 0, v4, s[80:81]
	v_cvt_pk_bf16_f32 v8, v8, v9
	v_cvt_pk_bf16_f32 v9, v10, v11
	v_cvt_pk_bf16_f32 v4, v4, v5
	v_cvt_pk_bf16_f32 v5, v6, v7
	v_add_u32_e32 v6, 0xf800, v95
	ds_write2_b64 v6, v[8:9], v[4:5] offset0:128 offset1:132
	ds_read_b128 v[4:7], v91 offset:27648
	ds_read_b128 v[8:11], v161 offset:9216
	ds_read_b128 v[12:15], v161 offset:11520
	ds_read_b128 v[220:223], v91 offset:27712
	ds_read_b128 v[16:19], v161 offset:9280
	ds_read_b128 v[224:227], v161 offset:11584
	s_waitcnt lgkmcnt(4)
	v_mfma_f32_16x16x32_bf16 v[8:11], v[8:11], v[4:7], 0
	s_waitcnt lgkmcnt(3)
	v_mfma_f32_16x16x32_bf16 v[4:7], v[12:15], v[4:7], 0
	s_nop 0
	s_nop 0
	s_waitcnt lgkmcnt(1)
	v_mfma_f32_16x16x32_bf16 v[8:11], v[16:19], v[220:223], v[8:11]
	s_nop 0
	s_waitcnt lgkmcnt(0)
	v_mfma_f32_16x16x32_bf16 v[4:7], v[224:227], v[220:223], v[4:7]
	v_mov_b32_e32 v12, s9
	s_nop 3
	v_cndmask_b32_e64 v12, v8, v12, s[28:29]
	v_cndmask_b32_e64 v8, v12, v8, s[20:21]
	v_cndmask_b32_e64 v9, 0, v9, s[20:21]
	v_cndmask_b32_e64 v12, v10, 0, s[30:31]
	v_cvt_pk_bf16_f32 v10, v8, v9
	v_mov_b32_e32 v8, s9
	v_cndmask_b32_e64 v8, v4, v8, s[36:37]
	v_cndmask_b32_e64 v11, v11, 0, s[34:35]
	v_cndmask_b32_e64 v4, v8, v4, s[24:25]
	v_cndmask_b32_e64 v5, 0, v5, s[24:25]
	v_cndmask_b32_e64 v6, v6, 0, s[38:39]
	v_cndmask_b32_e64 v7, v7, 0, s[40:41]
	v_cvt_pk_bf16_f32 v11, v12, v11
	v_cvt_pk_bf16_f32 v4, v4, v5
	v_cvt_pk_bf16_f32 v5, v6, v7
	ds_write2_b64 v96, v[10:11], v[4:5] offset1:4
	ds_read_b128 v[4:7], v91 offset:27648
	ds_read_b128 v[8:11], v161 offset:18432
	ds_read_b128 v[12:15], v161 offset:20736
	s_waitcnt lgkmcnt(1)
	v_mfma_f32_16x16x32_bf16 v[8:11], v[8:11], v[4:7], 0
	s_waitcnt lgkmcnt(0)
	v_mfma_f32_16x16x32_bf16 v[4:7], v[12:15], v[4:7], 0
	ds_read_b128 v[12:15], v91 offset:27712
	ds_read_b128 v[16:19], v161 offset:18496
	s_waitcnt lgkmcnt(0)
	v_mfma_f32_16x16x32_bf16 v[8:11], v[16:19], v[12:15], v[8:11]
	ds_read_b128 v[16:19], v161 offset:20800
	s_waitcnt lgkmcnt(0)
	v_mfma_f32_16x16x32_bf16 v[4:7], v[16:19], v[12:15], v[4:7]
	v_mov_b32_e32 v12, s9
	s_nop 3
	v_cndmask_b32_e64 v12, v8, v12, s[28:29]
	v_cndmask_b32_e64 v8, v12, v8, s[20:21]
	v_cndmask_b32_e64 v9, 0, v9, s[20:21]
	v_cndmask_b32_e64 v12, v10, 0, s[30:31]
	v_cvt_pk_bf16_f32 v10, v8, v9
	v_mov_b32_e32 v8, s9
	v_cndmask_b32_e64 v8, v4, v8, s[36:37]
	v_cndmask_b32_e64 v11, v11, 0, s[34:35]
	v_cndmask_b32_e64 v4, v8, v4, s[24:25]
	v_cndmask_b32_e64 v5, 0, v5, s[24:25]
	v_cndmask_b32_e64 v6, v6, 0, s[38:39]
	v_cndmask_b32_e64 v7, v7, 0, s[40:41]
	v_cvt_pk_bf16_f32 v11, v12, v11
	v_cvt_pk_bf16_f32 v4, v4, v5
	v_cvt_pk_bf16_f32 v5, v6, v7
	ds_write2_b64 v97, v[10:11], v[4:5] offset1:4
	s_waitcnt lgkmcnt(0)
	s_barrier
	ds_read_b128 v[4:7], v91 offset:55296
	ds_read_b128 v[8:11], v161 offset:64512
	ds_read_b128 v[12:15], v139 offset:64512
	s_waitcnt lgkmcnt(1)
	v_mfma_f32_16x16x32_bf16 v[8:11], v[8:11], v[4:7], 0
	s_waitcnt lgkmcnt(0)
	v_mfma_f32_16x16x32_bf16 v[4:7], v[12:15], v[4:7], 0
	ds_read_b128 v[12:15], v91 offset:55360
	ds_read_b128 v[16:19], v161 offset:64576
	s_waitcnt lgkmcnt(0)
	v_mfma_f32_16x16x32_bf16 v[8:11], v[16:19], v[12:15], v[8:11]
	ds_read_b128 v[16:19], v139 offset:64576
	s_waitcnt lgkmcnt(0)
	v_mfma_f32_16x16x32_bf16 v[4:7], v[16:19], v[12:15], v[4:7]
	s_nop 4
	v_cvt_pk_bf16_f32 v8, v8, v9
	v_cvt_pk_bf16_f32 v9, v10, v11
	s_nop 0
	v_cvt_pk_bf16_f32 v4, v4, v5
	v_cvt_pk_bf16_f32 v5, v6, v7
	ds_write2_b64 v140, v[8:9], v[4:5] offset1:4
	s_and_saveexec_b64 s[100:101], s[98:99]
	ds_write2_b64 v212, v[214:215], v[214:215] offset1:1
	s_mov_b64 exec, s[100:101]
	s_mov_b64 s[12:13], exec
	v_readlane_b32 s14, v244, 49
	v_readlane_b32 s15, v244, 50
	s_and_b64 s[14:15], s[12:13], s[14:15]
	s_mov_b64 exec, s[14:15]
	s_cbranch_execz .LBB0_935
; #define LAS __attribute__((address_space(3)))
; __device__ __forceinline__ unsigned pk2(float lo, float hi) { const f32x2c v = {lo, hi}; const bf16x2c b = __builtin_convertvector(v, bf16x2c); return __builtin_bit_cast(unsigned, b); }
; __device__ __forceinline__ void chunk_pre(const Params& p, LAS unsigned char* lds, int item, int next_item, int tid, int wave, int lane, h16 (&raw)[48]) {
;     ...
;     if (tid < 64) {
;         const int r = tid >> 4, j = tid & 15; float x[16];
; #pragma unroll
;         for (int i = 0; i < 16; ++i) x[i] = 0.f;
; #pragma unroll
;         for (int i = 0; i < 16; ++i) {
;             const LAS float* mrow = Mab + (16 * r + i) * 64 + 16 * r;
;             float v = (i == j) ? 1.f : 0.f;
; #pragma unroll
;             for (int q = 0; q < (i + 3) / 4; ++q) { const f32x4 m4 = *(const LAS f32x4*)(mrow + 4 * q);
;                 v += (m4.x * x[4 * q] + m4.y * x[4 * q + 1]) + (m4.z * x[4 * q + 2] + m4.w * x[4 * q + 3]); }
;             x[i] = v; TD[r * 256 + i * 16 + j] = v; Tb[(16 * r + i) * MS + 16 * r + j] = (bf16_t)(pk2(v, 0.f) & 0xffffu);
	v_mbcnt_lo_u32_b32 v203, -1, 0
	v_mbcnt_hi_u32_b32 v203, -1, v203
	v_lshrrev_b32_e32 v20, 4, v203
	v_and_b32_e32 v202, 15, v203
	v_lshlrev_b32_e32 v200, 8, v203
	v_lshl_add_u32 v200, v20, 6, v200
	v_add_u32_e32 v200, 0x16800, v200
	ds_read_b128 v[184:187], v200 offset:0
	ds_read_b128 v[188:191], v200 offset:16
	ds_read_b128 v[192:195], v200 offset:32
	ds_read_b128 v[196:199], v200 offset:48
	v_lshlrev_b32_e32 v201, 2, v202
	v_lshl_add_u32 v201, v20, 10, v201
	v_add_u32_e32 v201, 0x1f000, v201
	v_lshlrev_b32_e32 v202, 1, v202
	v_mov_b32_e32 v203, 0x920
	v_mad_u32_u24 v202, v20, v203, v202
	v_mov_b32_e32 v4, v101
	v_mov_b32_e32 v5, v103
	v_mov_b32_e32 v6, v104
	v_mov_b32_e32 v7, v105
	v_mov_b32_e32 v8, v106
	v_mov_b32_e32 v9, v107
	v_mov_b32_e32 v10, v108
	v_mov_b32_e32 v11, v109
	v_mov_b32_e32 v12, v110
	v_mov_b32_e32 v13, v111
	v_mov_b32_e32 v14, v112
	v_mov_b32_e32 v15, v113
	v_mov_b32_e32 v16, v114
	v_mov_b32_e32 v17, v115
	v_mov_b32_e32 v18, v116
	v_mov_b32_e32 v19, v117
	s_waitcnt lgkmcnt(0)
	v_fmac_f32_dpp v5, v184, v4 row_newbcast:1 row_mask:0xf bank_mask:0xf
	v_fmac_f32_dpp v6, v184, v4 row_newbcast:2 row_mask:0xf bank_mask:0xf
	v_fmac_f32_dpp v6, v185, v5 row_newbcast:2 row_mask:0xf bank_mask:0xf
	v_fmac_f32_dpp v7, v184, v4 row_newbcast:3 row_mask:0xf bank_mask:0xf
	v_fmac_f32_dpp v7, v185, v5 row_newbcast:3 row_mask:0xf bank_mask:0xf
	v_fmac_f32_dpp v7, v186, v6 row_newbcast:3 row_mask:0xf bank_mask:0xf
	v_fmac_f32_dpp v8, v184, v4 row_newbcast:4 row_mask:0xf bank_mask:0xf
	v_fmac_f32_dpp v8, v185, v5 row_newbcast:4 row_mask:0xf bank_mask:0xf
	v_fmac_f32_dpp v8, v186, v6 row_newbcast:4 row_mask:0xf bank_mask:0xf
	v_fmac_f32_dpp v8, v187, v7 row_newbcast:4 row_mask:0xf bank_mask:0xf
	v_fmac_f32_dpp v9, v184, v4 row_newbcast:5 row_mask:0xf bank_mask:0xf
	v_fmac_f32_dpp v9, v185, v5 row_newbcast:5 row_mask:0xf bank_mask:0xf
	v_fmac_f32_dpp v9, v186, v6 row_newbcast:5 row_mask:0xf bank_mask:0xf
	v_fmac_f32_dpp v9, v187, v7 row_newbcast:5 row_mask:0xf bank_mask:0xf
	v_fmac_f32_dpp v9, v188, v8 row_newbcast:5 row_mask:0xf bank_mask:0xf
	v_fmac_f32_dpp v10, v184, v4 row_newbcast:6 row_mask:0xf bank_mask:0xf
	v_fmac_f32_dpp v10, v185, v5 row_newbcast:6 row_mask:0xf bank_mask:0xf
	v_fmac_f32_dpp v10, v186, v6 row_newbcast:6 row_mask:0xf bank_mask:0xf
	v_fmac_f32_dpp v10, v187, v7 row_newbcast:6 row_mask:0xf bank_mask:0xf
	v_fmac_f32_dpp v10, v188, v8 row_newbcast:6 row_mask:0xf bank_mask:0xf
	v_fmac_f32_dpp v10, v189, v9 row_newbcast:6 row_mask:0xf bank_mask:0xf
	v_fmac_f32_dpp v11, v184, v4 row_newbcast:7 row_mask:0xf bank_mask:0xf
	v_fmac_f32_dpp v11, v185, v5 row_newbcast:7 row_mask:0xf bank_mask:0xf
	v_fmac_f32_dpp v11, v186, v6 row_newbcast:7 row_mask:0xf bank_mask:0xf
	v_fmac_f32_dpp v11, v187, v7 row_newbcast:7 row_mask:0xf bank_mask:0xf
	v_fmac_f32_dpp v11, v188, v8 row_newbcast:7 row_mask:0xf bank_mask:0xf
	v_fmac_f32_dpp v11, v189, v9 row_newbcast:7 row_mask:0xf bank_mask:0xf
	v_fmac_f32_dpp v11, v190, v10 row_newbcast:7 row_mask:0xf bank_mask:0xf
	v_fmac_f32_dpp v12, v184, v4 row_newbcast:8 row_mask:0xf bank_mask:0xf
	v_fmac_f32_dpp v12, v185, v5 row_newbcast:8 row_mask:0xf bank_mask:0xf
	v_fmac_f32_dpp v12, v186, v6 row_newbcast:8 row_mask:0xf bank_mask:0xf
	v_fmac_f32_dpp v12, v187, v7 row_newbcast:8 row_mask:0xf bank_mask:0xf
	v_fmac_f32_dpp v12, v188, v8 row_newbcast:8 row_mask:0xf bank_mask:0xf
	v_fmac_f32_dpp v12, v189, v9 row_newbcast:8 row_mask:0xf bank_mask:0xf
	v_fmac_f32_dpp v12, v190, v10 row_newbcast:8 row_mask:0xf bank_mask:0xf
	v_fmac_f32_dpp v12, v191, v11 row_newbcast:8 row_mask:0xf bank_mask:0xf
	v_fmac_f32_dpp v13, v184, v4 row_newbcast:9 row_mask:0xf bank_mask:0xf
	v_fmac_f32_dpp v13, v185, v5 row_newbcast:9 row_mask:0xf bank_mask:0xf
	v_fmac_f32_dpp v13, v186, v6 row_newbcast:9 row_mask:0xf bank_mask:0xf
	v_fmac_f32_dpp v13, v187, v7 row_newbcast:9 row_mask:0xf bank_mask:0xf
	v_fmac_f32_dpp v13, v188, v8 row_newbcast:9 row_mask:0xf bank_mask:0xf
	v_fmac_f32_dpp v13, v189, v9 row_newbcast:9 row_mask:0xf bank_mask:0xf
	v_fmac_f32_dpp v13, v190, v10 row_newbcast:9 row_mask:0xf bank_mask:0xf
	v_fmac_f32_dpp v13, v191, v11 row_newbcast:9 row_mask:0xf bank_mask:0xf
	v_fmac_f32_dpp v13, v192, v12 row_newbcast:9 row_mask:0xf bank_mask:0xf
	v_fmac_f32_dpp v14, v184, v4 row_newbcast:10 row_mask:0xf bank_mask:0xf
	v_fmac_f32_dpp v14, v185, v5 row_newbcast:10 row_mask:0xf bank_mask:0xf
	v_fmac_f32_dpp v14, v186, v6 row_newbcast:10 row_mask:0xf bank_mask:0xf
	v_fmac_f32_dpp v14, v187, v7 row_newbcast:10 row_mask:0xf bank_mask:0xf
	v_fmac_f32_dpp v14, v188, v8 row_newbcast:10 row_mask:0xf bank_mask:0xf
	v_fmac_f32_dpp v14, v189, v9 row_newbcast:10 row_mask:0xf bank_mask:0xf
	v_fmac_f32_dpp v14, v190, v10 row_newbcast:10 row_mask:0xf bank_mask:0xf
	v_fmac_f32_dpp v14, v191, v11 row_newbcast:10 row_mask:0xf bank_mask:0xf
	v_fmac_f32_dpp v14, v192, v12 row_newbcast:10 row_mask:0xf bank_mask:0xf
	v_fmac_f32_dpp v14, v193, v13 row_newbcast:10 row_mask:0xf bank_mask:0xf
	v_fmac_f32_dpp v15, v184, v4 row_newbcast:11 row_mask:0xf bank_mask:0xf
	v_fmac_f32_dpp v15, v185, v5 row_newbcast:11 row_mask:0xf bank_mask:0xf
	v_fmac_f32_dpp v15, v186, v6 row_newbcast:11 row_mask:0xf bank_mask:0xf
	v_fmac_f32_dpp v15, v187, v7 row_newbcast:11 row_mask:0xf bank_mask:0xf
	v_fmac_f32_dpp v15, v188, v8 row_newbcast:11 row_mask:0xf bank_mask:0xf
	v_fmac_f32_dpp v15, v189, v9 row_newbcast:11 row_mask:0xf bank_mask:0xf
	v_fmac_f32_dpp v15, v190, v10 row_newbcast:11 row_mask:0xf bank_mask:0xf
	v_fmac_f32_dpp v15, v191, v11 row_newbcast:11 row_mask:0xf bank_mask:0xf
	v_fmac_f32_dpp v15, v192, v12 row_newbcast:11 row_mask:0xf bank_mask:0xf
; #define LAS __attribute__((address_space(3)))
; __device__ __forceinline__ unsigned pk2(float lo, float hi) { const f32x2c v = {lo, hi}; const bf16x2c b = __builtin_convertvector(v, bf16x2c); return __builtin_bit_cast(unsigned, b); }
; __device__ __forceinline__ void chunk_pre(const Params& p, LAS unsigned char* lds, int item, int next_item, int tid, int wave, int lane, h16 (&raw)[48]) {
;     ...
;         for (int i = 0; i < 16; ++i) {
;             const LAS float* mrow = Mab + (16 * r + i) * 64 + 16 * r;
;             float v = (i == j) ? 1.f : 0.f;
; #pragma unroll
;             for (int q = 0; q < (i + 3) / 4; ++q) { const f32x4 m4 = *(const LAS f32x4*)(mrow + 4 * q);
;                 v += (m4.x * x[4 * q] + m4.y * x[4 * q + 1]) + (m4.z * x[4 * q + 2] + m4.w * x[4 * q + 3]); }
;             x[i] = v; TD[r * 256 + i * 16 + j] = v; Tb[(16 * r + i) * MS + 16 * r + j] = (bf16_t)(pk2(v, 0.f) & 0xffffu);
;         }
	v_fmac_f32_dpp v15, v193, v13 row_newbcast:11 row_mask:0xf bank_mask:0xf
	v_fmac_f32_dpp v15, v194, v14 row_newbcast:11 row_mask:0xf bank_mask:0xf
	v_fmac_f32_dpp v16, v184, v4 row_newbcast:12 row_mask:0xf bank_mask:0xf
	v_fmac_f32_dpp v16, v185, v5 row_newbcast:12 row_mask:0xf bank_mask:0xf
	v_fmac_f32_dpp v16, v186, v6 row_newbcast:12 row_mask:0xf bank_mask:0xf
	v_fmac_f32_dpp v16, v187, v7 row_newbcast:12 row_mask:0xf bank_mask:0xf
	v_fmac_f32_dpp v16, v188, v8 row_newbcast:12 row_mask:0xf bank_mask:0xf
	v_fmac_f32_dpp v16, v189, v9 row_newbcast:12 row_mask:0xf bank_mask:0xf
	v_fmac_f32_dpp v16, v190, v10 row_newbcast:12 row_mask:0xf bank_mask:0xf
	v_fmac_f32_dpp v16, v191, v11 row_newbcast:12 row_mask:0xf bank_mask:0xf
	v_fmac_f32_dpp v16, v192, v12 row_newbcast:12 row_mask:0xf bank_mask:0xf
	v_fmac_f32_dpp v16, v193, v13 row_newbcast:12 row_mask:0xf bank_mask:0xf
	v_fmac_f32_dpp v16, v194, v14 row_newbcast:12 row_mask:0xf bank_mask:0xf
	v_fmac_f32_dpp v16, v195, v15 row_newbcast:12 row_mask:0xf bank_mask:0xf
	v_fmac_f32_dpp v17, v184, v4 row_newbcast:13 row_mask:0xf bank_mask:0xf
	v_fmac_f32_dpp v17, v185, v5 row_newbcast:13 row_mask:0xf bank_mask:0xf
	v_fmac_f32_dpp v17, v186, v6 row_newbcast:13 row_mask:0xf bank_mask:0xf
	v_fmac_f32_dpp v17, v187, v7 row_newbcast:13 row_mask:0xf bank_mask:0xf
	v_fmac_f32_dpp v17, v188, v8 row_newbcast:13 row_mask:0xf bank_mask:0xf
	v_fmac_f32_dpp v17, v189, v9 row_newbcast:13 row_mask:0xf bank_mask:0xf
	v_fmac_f32_dpp v17, v190, v10 row_newbcast:13 row_mask:0xf bank_mask:0xf
	v_fmac_f32_dpp v17, v191, v11 row_newbcast:13 row_mask:0xf bank_mask:0xf
	v_fmac_f32_dpp v17, v192, v12 row_newbcast:13 row_mask:0xf bank_mask:0xf
	v_fmac_f32_dpp v17, v193, v13 row_newbcast:13 row_mask:0xf bank_mask:0xf
	v_fmac_f32_dpp v17, v194, v14 row_newbcast:13 row_mask:0xf bank_mask:0xf
	v_fmac_f32_dpp v17, v195, v15 row_newbcast:13 row_mask:0xf bank_mask:0xf
	v_fmac_f32_dpp v17, v196, v16 row_newbcast:13 row_mask:0xf bank_mask:0xf
	v_fmac_f32_dpp v18, v184, v4 row_newbcast:14 row_mask:0xf bank_mask:0xf
	v_fmac_f32_dpp v18, v185, v5 row_newbcast:14 row_mask:0xf bank_mask:0xf
	v_fmac_f32_dpp v18, v186, v6 row_newbcast:14 row_mask:0xf bank_mask:0xf
	v_fmac_f32_dpp v18, v187, v7 row_newbcast:14 row_mask:0xf bank_mask:0xf
	v_fmac_f32_dpp v18, v188, v8 row_newbcast:14 row_mask:0xf bank_mask:0xf
	v_fmac_f32_dpp v18, v189, v9 row_newbcast:14 row_mask:0xf bank_mask:0xf
	v_fmac_f32_dpp v18, v190, v10 row_newbcast:14 row_mask:0xf bank_mask:0xf
	v_fmac_f32_dpp v18, v191, v11 row_newbcast:14 row_mask:0xf bank_mask:0xf
	v_fmac_f32_dpp v18, v192, v12 row_newbcast:14 row_mask:0xf bank_mask:0xf
	v_fmac_f32_dpp v18, v193, v13 row_newbcast:14 row_mask:0xf bank_mask:0xf
	v_fmac_f32_dpp v18, v194, v14 row_newbcast:14 row_mask:0xf bank_mask:0xf
	v_fmac_f32_dpp v18, v195, v15 row_newbcast:14 row_mask:0xf bank_mask:0xf
	v_fmac_f32_dpp v18, v196, v16 row_newbcast:14 row_mask:0xf bank_mask:0xf
	v_fmac_f32_dpp v18, v197, v17 row_newbcast:14 row_mask:0xf bank_mask:0xf
	v_fmac_f32_dpp v19, v184, v4 row_newbcast:15 row_mask:0xf bank_mask:0xf
	v_fmac_f32_dpp v19, v185, v5 row_newbcast:15 row_mask:0xf bank_mask:0xf
	v_fmac_f32_dpp v19, v186, v6 row_newbcast:15 row_mask:0xf bank_mask:0xf
	v_fmac_f32_dpp v19, v187, v7 row_newbcast:15 row_mask:0xf bank_mask:0xf
	v_fmac_f32_dpp v19, v188, v8 row_newbcast:15 row_mask:0xf bank_mask:0xf
	v_fmac_f32_dpp v19, v189, v9 row_newbcast:15 row_mask:0xf bank_mask:0xf
	v_fmac_f32_dpp v19, v190, v10 row_newbcast:15 row_mask:0xf bank_mask:0xf
	v_fmac_f32_dpp v19, v191, v11 row_newbcast:15 row_mask:0xf bank_mask:0xf
	v_fmac_f32_dpp v19, v192, v12 row_newbcast:15 row_mask:0xf bank_mask:0xf
	v_fmac_f32_dpp v19, v193, v13 row_newbcast:15 row_mask:0xf bank_mask:0xf
	v_fmac_f32_dpp v19, v194, v14 row_newbcast:15 row_mask:0xf bank_mask:0xf
	v_fmac_f32_dpp v19, v195, v15 row_newbcast:15 row_mask:0xf bank_mask:0xf
	v_fmac_f32_dpp v19, v196, v16 row_newbcast:15 row_mask:0xf bank_mask:0xf
	v_fmac_f32_dpp v19, v197, v17 row_newbcast:15 row_mask:0xf bank_mask:0xf
	v_fmac_f32_dpp v19, v198, v18 row_newbcast:15 row_mask:0xf bank_mask:0xf
	ds_write_b32 v201, v4 offset:0
	v_cvt_pk_bf16_f32 v20, v4, v4
	ds_write_b16 v202, v20 offset:0
	ds_write_b32 v201, v5 offset:64
	v_cvt_pk_bf16_f32 v20, v5, v5
	ds_write_b16 v202, v20 offset:144
	ds_write_b32 v201, v6 offset:128
	v_cvt_pk_bf16_f32 v20, v6, v6
	ds_write_b16 v202, v20 offset:288
	ds_write_b32 v201, v7 offset:192
	v_cvt_pk_bf16_f32 v20, v7, v7
	ds_write_b16 v202, v20 offset:432
	ds_write_b32 v201, v8 offset:256
	v_cvt_pk_bf16_f32 v20, v8, v8
	ds_write_b16 v202, v20 offset:576
	ds_write_b32 v201, v9 offset:320
	v_cvt_pk_bf16_f32 v20, v9, v9
	ds_write_b16 v202, v20 offset:720
	ds_write_b32 v201, v10 offset:384
	v_cvt_pk_bf16_f32 v20, v10, v10
	ds_write_b16 v202, v20 offset:864
	ds_write_b32 v201, v11 offset:448
	v_cvt_pk_bf16_f32 v20, v11, v11
	ds_write_b16 v202, v20 offset:1008
	ds_write_b32 v201, v12 offset:512
	v_cvt_pk_bf16_f32 v20, v12, v12
	ds_write_b16 v202, v20 offset:1152
	ds_write_b32 v201, v13 offset:576
	v_cvt_pk_bf16_f32 v20, v13, v13
	ds_write_b16 v202, v20 offset:1296
	ds_write_b32 v201, v14 offset:640
	v_cvt_pk_bf16_f32 v20, v14, v14
	ds_write_b16 v202, v20 offset:1440
	ds_write_b32 v201, v15 offset:704
	v_cvt_pk_bf16_f32 v20, v15, v15
	ds_write_b16 v202, v20 offset:1584
	ds_write_b32 v201, v16 offset:768
	v_cvt_pk_bf16_f32 v20, v16, v16
	ds_write_b16 v202, v20 offset:1728
	ds_write_b32 v201, v17 offset:832
	v_cvt_pk_bf16_f32 v20, v17, v17
	ds_write_b16 v202, v20 offset:1872
	ds_write_b32 v201, v18 offset:896
	v_cvt_pk_bf16_f32 v20, v18, v18
	ds_write_b16 v202, v20 offset:2016
	ds_write_b32 v201, v19 offset:960
	v_cvt_pk_bf16_f32 v20, v19, v19
	ds_write_b16 v202, v20 offset:2160
; #define BAR_LDS() do { asm volatile("s_waitcnt lgkmcnt(0)" ::: "memory"); __builtin_amdgcn_s_barrier(); asm volatile("" ::: "memory"); } while (0)
; __device__ __forceinline__ unsigned pk2(float lo, float hi) { const f32x2c v = {lo, hi}; const bf16x2c b = __builtin_convertvector(v, bf16x2c); return __builtin_bit_cast(unsigned, b); }
; #define TDW(r_, wp) ({ const LAS float* tr_ = TD + (r_) * 256 + i * 16; const LAS float* bp_ = (wp) + j; float a_ = 0.f; \
;         _Pragma("unroll") for (int u4 = 0; u4 < 4; ++u4) { const f32x4 t4 = *(const LAS f32x4*)(tr_ + 4 * u4); \
;             a_ += (t4.x * bp_[(4 * u4) * 16] + t4.y * bp_[(4 * u4 + 1) * 16]) + (t4.z * bp_[(4 * u4 + 2) * 16] + t4.w * bp_[(4 * u4 + 3) * 16]); } a_; })
; __device__ __forceinline__ void chunk_pre(const Params& p, LAS unsigned char* lds, int item, int next_item, int tid, int wave, int lane, h16 (&raw)[48]) {
;     ...
;     for (int e = tid; e < 3 * 256; e += 512) { const int bk = e >> 8, i = (e >> 4) & 15, j = e & 15; Wf[bk * 256 + i * 16 + j] = M16(bk + 1, bk, TD + bk * 256); }
;     BAR_LDS();
;     for (int e = tid; e < 3 * 256; e += 512) { const int bk = e >> 8, i = (e >> 4) & 15, j = e & 15; const float t = TDW(bk + 1, Wf + bk * 256);
;         Toff[bk * 256 + i * 16 + j] = t; Tb[(16 * (bk + 1) + i) * MS + 16 * bk + j] = (bf16_t)(pk2(t, 0.f) & 0xffffu); }
;     BAR_LDS();
;     { const int bk = tid >> 8, i = (tid >> 4) & 15, j = tid & 15; Wf[bk * 256 + i * 16 + j] = M16(bk + 2, bk, TD + bk * 256) + M16(bk + 2, bk + 1, Toff + bk * 256); }
;     BAR_LDS();
;     { const int bk = tid >> 8, i = (tid >> 4) & 15, j = tid & 15; const float t = TDW(bk + 2, Wf + bk * 256);
;       Toff[(3 + bk) * 256 + i * 16 + j] = t; Tb[(16 * (bk + 2) + i) * MS + 16 * bk + j] = (bf16_t)(pk2(t, 0.f) & 0xffffu); }
;     BAR_LDS();
;     if (tid < 256) { const int i = tid >> 4, j = tid & 15; Wf[i * 16 + j] = M16(3, 0, TD) + M16(3, 1, Toff) + M16(3, 2, Toff + 3 * 256); }
;     BAR_LDS();
;     if (tid < 256) { const int i = tid >> 4, j = tid & 15; const float t = TDW(3, Wf); Tb[(48 + i) * MS + j] = (bf16_t)(pk2(t, 0.f) & 0xffffu); }
;     BAR_LDS();
.LBB0_935:
	s_or_b64 exec, exec, s[12:13]
	s_waitcnt lgkmcnt(0)
	s_barrier
	v_readlane_b32 s100, v244, 14
	v_mbcnt_lo_u32_b32 v9, -1, 0
	v_mbcnt_hi_u32_b32 v9, -1, v9
	s_nop 1
	s_cmp_gt_u32 s100, 2
	s_cbranch_scc1 .Llev_done
	v_and_b32_e32 v10, 15, v9
	v_lshrrev_b32_e32 v11, 4, v9
	v_lshlrev_b32_e32 v12, 2, v11
	v_lshlrev_b32_e32 v13, 2, v10
	v_lshl_add_u32 v4, v10, 8, v12
	v_add_u32_e32 v4, 0x16800, v4
	v_lshl_add_u32 v5, v10, 6, v12
	v_add_u32_e32 v5, 0x1f000, v5
	v_lshl_add_u32 v6, v11, 6, v13
	v_add_u32_e32 v6, 0x1f000, v6
	v_lshl_add_u32 v7, v11, 8, v13
	v_add_u32_e32 v7, 0x1f000, v7
	v_lshlrev_b32_e32 v14, 1, v10
	v_mov_b32_e32 v15, 0x240
	v_mad_u32_u24 v8, v11, v15, v14
	s_cmp_eq_u32 s100, 1
	s_cbranch_scc1 .Llev_col1
	s_cmp_eq_u32 s100, 2
	s_cbranch_scc1 .Llev_col2
	ds_read_b32 v10, v4 offset:4096
	ds_read_b32 v11, v4 offset:4112
	ds_read_b32 v12, v4 offset:4128
	ds_read_b32 v13, v4 offset:4144
	ds_read_b32 v14, v6 offset:0
	ds_read_b32 v15, v6 offset:256
	ds_read_b32 v16, v6 offset:512
	ds_read_b32 v17, v6 offset:768
	s_waitcnt lgkmcnt(0)
	v_mfma_f32_16x16x4_f32 v[36:39], v10, v14, 0
	v_mfma_f32_16x16x4_f32 v[36:39], v11, v15, v[36:39]
	v_mfma_f32_16x16x4_f32 v[36:39], v12, v16, v[36:39]
	v_mfma_f32_16x16x4_f32 v[36:39], v13, v17, v[36:39]
	ds_read_b32 v18, v5 offset:1024
	ds_read_b32 v19, v5 offset:1040
	ds_read_b32 v34, v5 offset:1056
	ds_read_b32 v35, v5 offset:1072
	s_nop 7
	s_nop 1
	ds_write_b32 v7, v36 offset:10240
	ds_write_b32 v7, v37 offset:10304
	ds_write_b32 v7, v38 offset:10368
	ds_write_b32 v7, v39 offset:10432
	ds_read_b32 v164, v6 offset:10240
	ds_read_b32 v165, v6 offset:10496
	ds_read_b32 v166, v6 offset:10752
	ds_read_b32 v167, v6 offset:11008
	s_waitcnt lgkmcnt(0)
	v_mfma_f32_16x16x4_f32 v[36:39], v18, v164, 0
	v_mfma_f32_16x16x4_f32 v[36:39], v19, v165, v[36:39]
	v_mfma_f32_16x16x4_f32 v[36:39], v34, v166, v[36:39]
	v_mfma_f32_16x16x4_f32 v[36:39], v35, v167, v[36:39]
	s_nop 7
	s_nop 1
	ds_write_b32 v7, v36 offset:4096
	ds_write_b32 v7, v37 offset:4160
	ds_write_b32 v7, v38 offset:4224
	ds_write_b32 v7, v39 offset:4288
	v_cvt_pk_bf16_f32 v9, v36, v36
	ds_write_b16 v8, v9 offset:2304
	v_cvt_pk_bf16_f32 v9, v37, v37
	ds_write_b16 v8, v9 offset:2448
	v_cvt_pk_bf16_f32 v9, v38, v38
	ds_write_b16 v8, v9 offset:2592
	v_cvt_pk_bf16_f32 v9, v39, v39
	ds_write_b16 v8, v9 offset:2736
	ds_read_b32 v10, v4 offset:8192
	ds_read_b32 v11, v4 offset:8208
	ds_read_b32 v12, v4 offset:8224
	ds_read_b32 v13, v4 offset:8240
	ds_read_b32 v14, v6 offset:0
	ds_read_b32 v15, v6 offset:256
	ds_read_b32 v16, v6 offset:512
	ds_read_b32 v17, v6 offset:768
	ds_read_b32 v18, v4 offset:8256
	ds_read_b32 v19, v4 offset:8272
	ds_read_b32 v34, v4 offset:8288
	ds_read_b32 v35, v4 offset:8304
	ds_read_b32 v164, v6 offset:4096
	ds_read_b32 v165, v6 offset:4352
	ds_read_b32 v166, v6 offset:4608
	ds_read_b32 v167, v6 offset:4864
	s_waitcnt lgkmcnt(8)
	v_mfma_f32_16x16x4_f32 v[36:39], v10, v14, 0
	v_mfma_f32_16x16x4_f32 v[36:39], v11, v15, v[36:39]
	v_mfma_f32_16x16x4_f32 v[36:39], v12, v16, v[36:39]
	v_mfma_f32_16x16x4_f32 v[36:39], v13, v17, v[36:39]
	s_waitcnt lgkmcnt(0)
	v_mfma_f32_16x16x4_f32 v[36:39], v18, v164, v[36:39]
	v_mfma_f32_16x16x4_f32 v[36:39], v19, v165, v[36:39]
	v_mfma_f32_16x16x4_f32 v[36:39], v34, v166, v[36:39]
	v_mfma_f32_16x16x4_f32 v[36:39], v35, v167, v[36:39]
	ds_read_b32 v10, v5 offset:2048
	ds_read_b32 v11, v5 offset:2064
	ds_read_b32 v12, v5 offset:2080
	ds_read_b32 v13, v5 offset:2096
	s_nop 7
	s_nop 1
	ds_write_b32 v7, v36 offset:10240
	ds_write_b32 v7, v37 offset:10304
	ds_write_b32 v7, v38 offset:10368
	ds_write_b32 v7, v39 offset:10432
	ds_read_b32 v14, v6 offset:10240
	ds_read_b32 v15, v6 offset:10496
	ds_read_b32 v16, v6 offset:10752
	ds_read_b32 v17, v6 offset:11008
	s_waitcnt lgkmcnt(0)
	v_mfma_f32_16x16x4_f32 v[36:39], v10, v14, 0
	v_mfma_f32_16x16x4_f32 v[36:39], v11, v15, v[36:39]
	v_mfma_f32_16x16x4_f32 v[36:39], v12, v16, v[36:39]
	v_mfma_f32_16x16x4_f32 v[36:39], v13, v17, v[36:39]
	s_nop 7
	s_nop 1
	ds_write_b32 v7, v36 offset:5120
	ds_write_b32 v7, v37 offset:5184
	ds_write_b32 v7, v38 offset:5248
	ds_write_b32 v7, v39 offset:5312
	v_cvt_pk_bf16_f32 v9, v36, v36
	ds_write_b16 v8, v9 offset:4608
	v_cvt_pk_bf16_f32 v9, v37, v37
	ds_write_b16 v8, v9 offset:4752
	v_cvt_pk_bf16_f32 v9, v38, v38
	ds_write_b16 v8, v9 offset:4896
	v_cvt_pk_bf16_f32 v9, v39, v39
	ds_write_b16 v8, v9 offset:5040
	ds_read_b32 v10, v4 offset:12288
	ds_read_b32 v11, v4 offset:12304
	ds_read_b32 v12, v4 offset:12320
	ds_read_b32 v13, v4 offset:12336
	ds_read_b32 v14, v6 offset:0
	ds_read_b32 v15, v6 offset:256
	ds_read_b32 v16, v6 offset:512
	ds_read_b32 v17, v6 offset:768
	ds_read_b32 v18, v4 offset:12352
	ds_read_b32 v19, v4 offset:12368
	ds_read_b32 v34, v4 offset:12384
	ds_read_b32 v35, v4 offset:12400
	ds_read_b32 v164, v6 offset:4096
	ds_read_b32 v165, v6 offset:4352
	ds_read_b32 v166, v6 offset:4608
	ds_read_b32 v167, v6 offset:4864
	s_waitcnt lgkmcnt(8)
	v_mfma_f32_16x16x4_f32 v[36:39], v10, v14, 0
	v_mfma_f32_16x16x4_f32 v[36:39], v11, v15, v[36:39]
	v_mfma_f32_16x16x4_f32 v[36:39], v12, v16, v[36:39]
	v_mfma_f32_16x16x4_f32 v[36:39], v13, v17, v[36:39]
	ds_read_b32 v10, v4 offset:12416
	ds_read_b32 v11, v4 offset:12432
	ds_read_b32 v12, v4 offset:12448
	ds_read_b32 v13, v4 offset:12464
	ds_read_b32 v14, v6 offset:5120
	ds_read_b32 v15, v6 offset:5376
	ds_read_b32 v16, v6 offset:5632
	ds_read_b32 v17, v6 offset:5888
	s_waitcnt lgkmcnt(8)
	v_mfma_f32_16x16x4_f32 v[36:39], v18, v164, v[36:39]
	v_mfma_f32_16x16x4_f32 v[36:39], v19, v165, v[36:39]
	v_mfma_f32_16x16x4_f32 v[36:39], v34, v166, v[36:39]
	v_mfma_f32_16x16x4_f32 v[36:39], v35, v167, v[36:39]
	s_waitcnt lgkmcnt(0)
	v_mfma_f32_16x16x4_f32 v[36:39], v10, v14, v[36:39]
	v_mfma_f32_16x16x4_f32 v[36:39], v11, v15, v[36:39]
	v_mfma_f32_16x16x4_f32 v[36:39], v12, v16, v[36:39]
	v_mfma_f32_16x16x4_f32 v[36:39], v13, v17, v[36:39]
	ds_read_b32 v18, v5 offset:3072
	ds_read_b32 v19, v5 offset:3088
	ds_read_b32 v34, v5 offset:3104
	ds_read_b32 v35, v5 offset:3120
	s_nop 7
	s_nop 1
	ds_write_b32 v7, v36 offset:10240
	ds_write_b32 v7, v37 offset:10304
	ds_write_b32 v7, v38 offset:10368
	ds_write_b32 v7, v39 offset:10432
	ds_read_b32 v164, v6 offset:10240
	ds_read_b32 v165, v6 offset:10496
	ds_read_b32 v166, v6 offset:10752
	ds_read_b32 v167, v6 offset:11008
	s_waitcnt lgkmcnt(0)
	v_mfma_f32_16x16x4_f32 v[36:39], v18, v164, 0
	v_mfma_f32_16x16x4_f32 v[36:39], v19, v165, v[36:39]
	v_mfma_f32_16x16x4_f32 v[36:39], v34, v166, v[36:39]
	v_mfma_f32_16x16x4_f32 v[36:39], v35, v167, v[36:39]
	s_nop 7
	s_nop 1
	v_cvt_pk_bf16_f32 v9, v36, v36
	ds_write_b16 v8, v9 offset:6912
	v_cvt_pk_bf16_f32 v9, v37, v37
	ds_write_b16 v8, v9 offset:7056
	v_cvt_pk_bf16_f32 v9, v38, v38
	ds_write_b16 v8, v9 offset:7200
	v_cvt_pk_bf16_f32 v9, v39, v39
	ds_write_b16 v8, v9 offset:7344
	s_branch .Llev_done
; #define BAR_LDS() do { asm volatile("s_waitcnt lgkmcnt(0)" ::: "memory"); __builtin_amdgcn_s_barrier(); asm volatile("" ::: "memory"); } while (0)
; __device__ __forceinline__ unsigned pk2(float lo, float hi) { const f32x2c v = {lo, hi}; const bf16x2c b = __builtin_convertvector(v, bf16x2c); return __builtin_bit_cast(unsigned, b); }
; #define TDW(r_, wp) ({ const LAS float* tr_ = TD + (r_) * 256 + i * 16; const LAS float* bp_ = (wp) + j; float a_ = 0.f; \
;         _Pragma("unroll") for (int u4 = 0; u4 < 4; ++u4) { const f32x4 t4 = *(const LAS f32x4*)(tr_ + 4 * u4); \
;             a_ += (t4.x * bp_[(4 * u4) * 16] + t4.y * bp_[(4 * u4 + 1) * 16]) + (t4.z * bp_[(4 * u4 + 2) * 16] + t4.w * bp_[(4 * u4 + 3) * 16]); } a_; })
; __device__ __forceinline__ void chunk_pre(const Params& p, LAS unsigned char* lds, int item, int next_item, int tid, int wave, int lane, h16 (&raw)[48]) {
;     ...
;     for (int e = tid; e < 3 * 256; e += 512) { const int bk = e >> 8, i = (e >> 4) & 15, j = e & 15; Wf[bk * 256 + i * 16 + j] = M16(bk + 1, bk, TD + bk * 256); }
;     BAR_LDS();
;     for (int e = tid; e < 3 * 256; e += 512) { const int bk = e >> 8, i = (e >> 4) & 15, j = e & 15; const float t = TDW(bk + 1, Wf + bk * 256);
;         Toff[bk * 256 + i * 16 + j] = t; Tb[(16 * (bk + 1) + i) * MS + 16 * bk + j] = (bf16_t)(pk2(t, 0.f) & 0xffffu); }
;     BAR_LDS();
;     { const int bk = tid >> 8, i = (tid >> 4) & 15, j = tid & 15; Wf[bk * 256 + i * 16 + j] = M16(bk + 2, bk, TD + bk * 256) + M16(bk + 2, bk + 1, Toff + bk * 256); }
;     BAR_LDS();
;     { const int bk = tid >> 8, i = (tid >> 4) & 15, j = tid & 15; const float t = TDW(bk + 2, Wf + bk * 256);
;       Toff[(3 + bk) * 256 + i * 16 + j] = t; Tb[(16 * (bk + 2) + i) * MS + 16 * bk + j] = (bf16_t)(pk2(t, 0.f) & 0xffffu); }
;     BAR_LDS();
;     if (tid < 256) { const int i = tid >> 4, j = tid & 15; Wf[i * 16 + j] = M16(3, 0, TD) + M16(3, 1, Toff) + M16(3, 2, Toff + 3 * 256); }
;     BAR_LDS();
;     if (tid < 256) { const int i = tid >> 4, j = tid & 15; const float t = TDW(3, Wf); Tb[(48 + i) * MS + j] = (bf16_t)(pk2(t, 0.f) & 0xffffu); }
;     BAR_LDS();
.Llev_col1:
	ds_read_b32 v10, v4 offset:8256
	ds_read_b32 v11, v4 offset:8272
	ds_read_b32 v12, v4 offset:8288
	ds_read_b32 v13, v4 offset:8304
	ds_read_b32 v14, v6 offset:1024
	ds_read_b32 v15, v6 offset:1280
	ds_read_b32 v16, v6 offset:1536
	ds_read_b32 v17, v6 offset:1792
	s_waitcnt lgkmcnt(0)
	v_mfma_f32_16x16x4_f32 v[36:39], v10, v14, 0
	v_mfma_f32_16x16x4_f32 v[36:39], v11, v15, v[36:39]
	v_mfma_f32_16x16x4_f32 v[36:39], v12, v16, v[36:39]
	v_mfma_f32_16x16x4_f32 v[36:39], v13, v17, v[36:39]
	ds_read_b32 v18, v5 offset:2048
	ds_read_b32 v19, v5 offset:2064
	ds_read_b32 v34, v5 offset:2080
	ds_read_b32 v35, v5 offset:2096
	s_nop 7
	s_nop 1
	ds_write_b32 v7, v36 offset:11264
	ds_write_b32 v7, v37 offset:11328
	ds_write_b32 v7, v38 offset:11392
	ds_write_b32 v7, v39 offset:11456
	ds_read_b32 v164, v6 offset:11264
	ds_read_b32 v165, v6 offset:11520
	ds_read_b32 v166, v6 offset:11776
	ds_read_b32 v167, v6 offset:12032
	s_waitcnt lgkmcnt(0)
	v_mfma_f32_16x16x4_f32 v[36:39], v18, v164, 0
	v_mfma_f32_16x16x4_f32 v[36:39], v19, v165, v[36:39]
	v_mfma_f32_16x16x4_f32 v[36:39], v34, v166, v[36:39]
	v_mfma_f32_16x16x4_f32 v[36:39], v35, v167, v[36:39]
	s_nop 7
	s_nop 1
	ds_write_b32 v7, v36 offset:6144
	ds_write_b32 v7, v37 offset:6208
	ds_write_b32 v7, v38 offset:6272
	ds_write_b32 v7, v39 offset:6336
	v_cvt_pk_bf16_f32 v9, v36, v36
	ds_write_b16 v8, v9 offset:4640
	v_cvt_pk_bf16_f32 v9, v37, v37
	ds_write_b16 v8, v9 offset:4784
	v_cvt_pk_bf16_f32 v9, v38, v38
	ds_write_b16 v8, v9 offset:4928
	v_cvt_pk_bf16_f32 v9, v39, v39
	ds_write_b16 v8, v9 offset:5072
	ds_read_b32 v10, v4 offset:12352
	ds_read_b32 v11, v4 offset:12368
	ds_read_b32 v12, v4 offset:12384
	ds_read_b32 v13, v4 offset:12400
	ds_read_b32 v14, v6 offset:1024
	ds_read_b32 v15, v6 offset:1280
	ds_read_b32 v16, v6 offset:1536
	ds_read_b32 v17, v6 offset:1792
	ds_read_b32 v18, v4 offset:12416
	ds_read_b32 v19, v4 offset:12432
	ds_read_b32 v34, v4 offset:12448
	ds_read_b32 v35, v4 offset:12464
	ds_read_b32 v164, v6 offset:6144
	ds_read_b32 v165, v6 offset:6400
	ds_read_b32 v166, v6 offset:6656
	ds_read_b32 v167, v6 offset:6912
	s_waitcnt lgkmcnt(8)
	v_mfma_f32_16x16x4_f32 v[36:39], v10, v14, 0
	v_mfma_f32_16x16x4_f32 v[36:39], v11, v15, v[36:39]
	v_mfma_f32_16x16x4_f32 v[36:39], v12, v16, v[36:39]
	v_mfma_f32_16x16x4_f32 v[36:39], v13, v17, v[36:39]
	s_waitcnt lgkmcnt(0)
	v_mfma_f32_16x16x4_f32 v[36:39], v18, v164, v[36:39]
	v_mfma_f32_16x16x4_f32 v[36:39], v19, v165, v[36:39]
	v_mfma_f32_16x16x4_f32 v[36:39], v34, v166, v[36:39]
	v_mfma_f32_16x16x4_f32 v[36:39], v35, v167, v[36:39]
	ds_read_b32 v10, v5 offset:3072
	ds_read_b32 v11, v5 offset:3088
	ds_read_b32 v12, v5 offset:3104
	ds_read_b32 v13, v5 offset:3120
	s_nop 7
	s_nop 1
	ds_write_b32 v7, v36 offset:11264
	ds_write_b32 v7, v37 offset:11328
	ds_write_b32 v7, v38 offset:11392
	ds_write_b32 v7, v39 offset:11456
	ds_read_b32 v14, v6 offset:11264
	ds_read_b32 v15, v6 offset:11520
	ds_read_b32 v16, v6 offset:11776
	ds_read_b32 v17, v6 offset:12032
	s_waitcnt lgkmcnt(0)
	v_mfma_f32_16x16x4_f32 v[36:39], v10, v14, 0
	v_mfma_f32_16x16x4_f32 v[36:39], v11, v15, v[36:39]
	v_mfma_f32_16x16x4_f32 v[36:39], v12, v16, v[36:39]
	v_mfma_f32_16x16x4_f32 v[36:39], v13, v17, v[36:39]
	s_nop 7
	s_nop 1
	v_cvt_pk_bf16_f32 v9, v36, v36
	ds_write_b16 v8, v9 offset:6944
	v_cvt_pk_bf16_f32 v9, v37, v37
	ds_write_b16 v8, v9 offset:7088
	v_cvt_pk_bf16_f32 v9, v38, v38
	ds_write_b16 v8, v9 offset:7232
	v_cvt_pk_bf16_f32 v9, v39, v39
	ds_write_b16 v8, v9 offset:7376
	s_branch .Llev_done
.Llev_col2:
	ds_read_b32 v10, v4 offset:12416
	ds_read_b32 v11, v4 offset:12432
	ds_read_b32 v12, v4 offset:12448
	ds_read_b32 v13, v4 offset:12464
	ds_read_b32 v14, v6 offset:2048
	ds_read_b32 v15, v6 offset:2304
	ds_read_b32 v16, v6 offset:2560
	ds_read_b32 v17, v6 offset:2816
	s_waitcnt lgkmcnt(0)
	v_mfma_f32_16x16x4_f32 v[36:39], v10, v14, 0
	v_mfma_f32_16x16x4_f32 v[36:39], v11, v15, v[36:39]
	v_mfma_f32_16x16x4_f32 v[36:39], v12, v16, v[36:39]
	v_mfma_f32_16x16x4_f32 v[36:39], v13, v17, v[36:39]
	ds_read_b32 v18, v5 offset:3072
	ds_read_b32 v19, v5 offset:3088
	ds_read_b32 v34, v5 offset:3104
	ds_read_b32 v35, v5 offset:3120
	s_nop 7
	s_nop 1
	ds_write_b32 v7, v36 offset:12288
	ds_write_b32 v7, v37 offset:12352
	ds_write_b32 v7, v38 offset:12416
	ds_write_b32 v7, v39 offset:12480
	ds_read_b32 v164, v6 offset:12288
	ds_read_b32 v165, v6 offset:12544
	ds_read_b32 v166, v6 offset:12800
	ds_read_b32 v167, v6 offset:13056
	s_waitcnt lgkmcnt(0)
	v_mfma_f32_16x16x4_f32 v[36:39], v18, v164, 0
	v_mfma_f32_16x16x4_f32 v[36:39], v19, v165, v[36:39]
	v_mfma_f32_16x16x4_f32 v[36:39], v34, v166, v[36:39]
	v_mfma_f32_16x16x4_f32 v[36:39], v35, v167, v[36:39]
	s_nop 7
	s_nop 1
	v_cvt_pk_bf16_f32 v9, v36, v36
	ds_write_b16 v8, v9 offset:6976
	v_cvt_pk_bf16_f32 v9, v37, v37
	ds_write_b16 v8, v9 offset:7120
	v_cvt_pk_bf16_f32 v9, v38, v38
	ds_write_b16 v8, v9 offset:7264
	v_cvt_pk_bf16_f32 v9, v39, v39
	ds_write_b16 v8, v9 offset:7408
.Llev_done:
	s_mov_b64 s[12:13], exec
	s_branch .LBB0_922

; #define LAS __attribute__((address_space(3)))
; __global__ void __launch_bounds__(512, 2) mega_fwd(Params p) {
;     extern __shared__ __attribute__((aligned(16))) unsigned char lds_raw[];
;     cg::grid_group grid = cg::this_grid();
;     LAS unsigned char* lds = (LAS unsigned char*)lds_raw;
;     const int wave = __builtin_amdgcn_readfirstlane((int)threadIdx.x >> 6);
	.amdhsa_kernel _Z8mega_fwd6Params
		.amdhsa_group_segment_fixed_size 0
		.amdhsa_private_segment_fixed_size 0
		.amdhsa_kernarg_size 504
		.amdhsa_user_sgpr_count 2
		.amdhsa_user_sgpr_dispatch_ptr 0
		.amdhsa_user_sgpr_queue_ptr 0
		.amdhsa_user_sgpr_kernarg_segment_ptr 1
		.amdhsa_user_sgpr_dispatch_id 0
		.amdhsa_user_sgpr_kernarg_preload_length 0
		.amdhsa_user_sgpr_kernarg_preload_offset 0
		.amdhsa_user_sgpr_private_segment_size 0
		.amdhsa_uses_dynamic_stack 0
		.amdhsa_enable_private_segment 0
		.amdhsa_system_sgpr_workgroup_id_x 1
		.amdhsa_system_sgpr_workgroup_id_y 0
		.amdhsa_system_sgpr_workgroup_id_z 0
		.amdhsa_system_sgpr_workgroup_info 0
		.amdhsa_system_vgpr_workitem_id 2
		.amdhsa_next_free_vgpr 248
		.amdhsa_next_free_sgpr 102
		.amdhsa_accum_offset 248
		.amdhsa_reserve_vcc 1
		.amdhsa_float_round_mode_32 0
		.amdhsa_float_round_mode_16_64 0
		.amdhsa_float_denorm_mode_32 3
		.amdhsa_float_denorm_mode_16_64 3
		.amdhsa_dx10_clamp 1
		.amdhsa_ieee_mode 1
		.amdhsa_fp16_overflow 0
		.amdhsa_tg_split 0
		.amdhsa_exception_fp_ieee_invalid_op 0
		.amdhsa_exception_fp_denorm_src 0
		.amdhsa_exception_fp_ieee_div_zero 0
		.amdhsa_exception_fp_ieee_overflow 0
		.amdhsa_exception_fp_ieee_underflow 0
		.amdhsa_exception_fp_ieee_inexact 0
		.amdhsa_exception_int_div_zero 0
	.end_amdhsa_kernel

; #define LAS __attribute__((address_space(3)))
; __global__ void __launch_bounds__(512, 2) mega_fwd(Params p) {
;     extern __shared__ __attribute__((aligned(16))) unsigned char lds_raw[];
;     cg::grid_group grid = cg::this_grid();
;     LAS unsigned char* lds = (LAS unsigned char*)lds_raw;
;     const int wave = __builtin_amdgcn_readfirstlane((int)threadIdx.x >> 6);
amdhsa.kernels:
  - .agpr_count:     0
    .args:
      - .offset:         0
        .size:           248
        .value_kind:     by_value
      - .offset:         248
        .size:           4
        .value_kind:     hidden_block_count_x
      - .offset:         252
        .size:           4
        .value_kind:     hidden_block_count_y
      - .offset:         256
        .size:           4
        .value_kind:     hidden_block_count_z
      - .offset:         260
        .size:           2
        .value_kind:     hidden_group_size_x
      - .offset:         262
        .size:           2
        .value_kind:     hidden_group_size_y
      - .offset:         264
        .size:           2
        .value_kind:     hidden_group_size_z
      - .offset:         266
        .size:           2
        .value_kind:     hidden_remainder_x
      - .offset:         268
        .size:           2
        .value_kind:     hidden_remainder_y
      - .offset:         270
        .size:           2
        .value_kind:     hidden_remainder_z
      - .offset:         288
        .size:           8
        .value_kind:     hidden_global_offset_x
      - .offset:         296
        .size:           8
        .value_kind:     hidden_global_offset_y
      - .offset:         304
        .size:           8
        .value_kind:     hidden_global_offset_z
      - .offset:         312
        .size:           2
        .value_kind:     hidden_grid_dims
      - .offset:         336
        .size:           8
        .value_kind:     hidden_multigrid_sync_arg
      - .offset:         368
        .size:           4
        .value_kind:     hidden_dynamic_lds_size
    .group_segment_fixed_size: 0
    .kernarg_segment_align: 8
    .kernarg_segment_size: 504
    .language:       OpenCL C
    .language_version:
      - 2
      - 0
    .max_flat_workgroup_size: 512
    .name:           _Z8mega_fwd6Params
    .private_segment_fixed_size: 0
    .sgpr_count:     108
    .sgpr_spill_count: 61
    .symbol:         _Z8mega_fwd6Params.kd
    .uniform_work_group_size: 1
    .uses_dynamic_stack: false
    .vgpr_count:     248
    .vgpr_spill_count: 0
    .wavefront_size: 64
